# conv stage 4: loop-invariant pointwise-bias loads hoisted out of the unit loop (removes two exposed vmcnt(0) per unit); on top of conv DPP wave_sum
# baseline (speedup 1.0000x reference)
.LBB0_720:
	s_cmpk_gt_i32 s96, 0x40f
	s_barrier
	s_cbranch_scc1 .LBB0_755
	v_and_b32_e32 v2, 15, v108
	v_lshl_or_b32 v34, s3, 5, v2
	v_and_b32_e32 v74, 48, v108
	v_mov_b32_e32 v75, 0
	v_lshl_add_u64 v[2:3], s[88:89], 0, v[74:75]
	s_mov_b64 s[0:1], 0x400000
	v_ashrrev_i32_e32 v35, 31, v34
	v_lshl_add_u64 v[36:37], v[2:3], 0, s[0:1]
	v_lshlrev_b64 v[2:3], 9, v[34:35]
	v_or_b32_e32 v34, 16, v34
	v_ashrrev_i32_e32 v35, 31, v34
	v_lshlrev_b64 v[34:35], 9, v[34:35]
	v_lshl_add_u64 v[30:31], v[36:37], 0, v[2:3]
	v_lshl_add_u64 v[62:63], v[36:37], 0, v[34:35]
	global_load_dwordx4 v[2:5], v[30:31], off
	global_load_dwordx4 v[6:9], v[30:31], off offset:64
	global_load_dwordx4 v[10:13], v[30:31], off offset:128
	global_load_dwordx4 v[14:17], v[30:31], off offset:192
	global_load_dwordx4 v[18:21], v[30:31], off offset:256
	global_load_dwordx4 v[22:25], v[30:31], off offset:320
	global_load_dwordx4 v[26:29], v[30:31], off offset:384
	s_nop 0
	global_load_dwordx4 v[30:33], v[30:31], off offset:448
	s_nop 0
	global_load_dwordx4 v[34:37], v[62:63], off
	global_load_dwordx4 v[38:41], v[62:63], off offset:64
	global_load_dwordx4 v[42:45], v[62:63], off offset:128
	global_load_dwordx4 v[46:49], v[62:63], off offset:192
	global_load_dwordx4 v[50:53], v[62:63], off offset:256
	global_load_dwordx4 v[54:57], v[62:63], off offset:320
	global_load_dwordx4 v[58:61], v[62:63], off offset:384
	s_nop 0
	global_load_dwordx4 v[62:65], v[62:63], off offset:448
	s_lshl_b32 s3, s96, 5
	s_lshl_b32 s26, s68, 5
	s_movk_i32 s27, 0x4000
	s_movk_i32 s28, 0x1640
	s_movk_i32 s29, 0x780
	s_movk_i32 s30, 0x580
	s_movk_i32 s31, 0x380
	s_movk_i32 s33, 0x180
	s_add_i32 s34, 0, 0x10000
	s_add_i32 s35, 0, 0x18000
	v_mov_b32_e32 v111, 0x3727c5ac
	s_mov_b32 s36, 0x800000
	s_movk_i32 s37, 0x7fff
	s_movk_i32 s38, 0x840
	s_movk_i32 s39, 0x210
	s_mov_b64 s[0:1], 0x5a00600
	v_mov_b32_e32 v112, 1
	s_lshr_b32 s40, s96, 2
	s_and_b32 s98, s96, 3
	s_lshl_b32 s98, s98, 6
	s_or_b32 s40, s40, s98
	s_xor_b32 s40, s40, 0x80
	s_lshl_b32 s3, s40, 5
	v_readlane_b32 s100, v239, 55
	v_readlane_b32 s101, v239, 56
	v_lshrrev_b32_e32 v180, 2, v1
	v_and_b32_e32 v180, 12, v180
	v_ashrrev_i32_e32 v181, 6, v1
	v_lshl_or_b32 v180, v181, 5, v180
	v_mov_b32_e32 v181, 0
	s_nop 1
	v_lshl_add_u64 v[180:181], v[180:181], 2, s[100:101]
	global_load_dwordx4 v[182:185], v[180:181], off
	global_load_dwordx4 v[186:189], v[180:181], off offset:64
	s_branch .LBB0_723
.LBB0_722:
	s_or_b64 exec, exec, s[4:5]
	v_readlane_b32 s4, v239, 1
	v_and_b32_e32 v74, 0x3fc, v100
	v_readlane_b32 s16, v239, 13
	v_readlane_b32 s17, v239, 14
	s_waitcnt lgkmcnt(0)
	s_barrier
	s_waitcnt vmcnt(0)
	v_lshl_add_u64 v[66:67], s[16:17], 0, v[74:75]
	v_add_co_u32_e32 v68, vcc, 0x1000, v66
	s_nop 1
	v_addc_co_u32_e32 v69, vcc, 0, v67, vcc
	v_add_co_u32_e32 v70, vcc, 0x2000, v66
	v_readlane_b32 s18, v239, 15
	s_nop 0
	v_addc_co_u32_e32 v71, vcc, 0, v67, vcc
	global_load_dword v123, v[68:69], off
	global_load_dword v122, v[68:69], off offset:1024
	global_load_dword v120, v[68:69], off offset:2048
	global_load_dword v118, v[68:69], off offset:3072
	global_load_dword v121, v[70:71], off
	global_load_dword v119, v[70:71], off offset:1024
	global_load_dword v117, v[70:71], off offset:2048
	global_load_dword v116, v[70:71], off offset:3072
	v_add_co_u32_e32 v68, vcc, 0x3000, v66
	v_readlane_b32 s19, v239, 16
	s_nop 0
	v_addc_co_u32_e32 v69, vcc, 0, v67, vcc
	v_add_co_u32_e32 v70, vcc, s27, v66
	v_readlane_b32 s5, v239, 2
	s_nop 0
	v_addc_co_u32_e32 v71, vcc, 0, v67, vcc
	global_load_dword v128, v74, s[16:17]
	global_load_dword v127, v74, s[16:17] offset:1024
	global_load_dword v126, v74, s[16:17] offset:2048
	global_load_dword v125, v74, s[16:17] offset:3072
	global_load_dword v124, v74, s[18:19]
	global_load_dword v147, v[68:69], off
	global_load_dword v146, v[68:69], off offset:1024
	global_load_dword v144, v[68:69], off offset:2048
	global_load_dword v142, v[68:69], off offset:3072
	global_load_dword v140, v[70:71], off
	global_load_dword v138, v[70:71], off offset:1024
	global_load_dword v136, v[70:71], off offset:2048
	global_load_dword v133, v[70:71], off offset:3072
	v_add_co_u32_e32 v68, vcc, 0x5000, v66
	v_readlane_b32 s6, v239, 3
	s_nop 0
	v_addc_co_u32_e32 v69, vcc, 0, v67, vcc
	v_add_co_u32_e32 v70, vcc, 0x6000, v66
	v_readlane_b32 s7, v239, 4
	s_nop 0
	v_addc_co_u32_e32 v71, vcc, 0, v67, vcc
	global_load_dword v145, v[68:69], off
	global_load_dword v143, v[68:69], off offset:1024
	global_load_dword v141, v[68:69], off offset:2048
	global_load_dword v139, v[68:69], off offset:3072
	global_load_dword v137, v[70:71], off
	global_load_dword v134, v[70:71], off offset:1024
	global_load_dword v131, v[70:71], off offset:2048
	global_load_dword v129, v[70:71], off offset:3072
	v_add_co_u32_e32 v66, vcc, 0x7000, v66
	v_readlane_b32 s8, v239, 5
	s_nop 0
	v_addc_co_u32_e32 v67, vcc, 0, v67, vcc
	global_load_dword v135, v[66:67], off
	global_load_dword v132, v[66:67], off offset:1024
	global_load_dword v130, v[66:67], off offset:2048
	v_lshlrev_b32_e32 v66, 6, v114
	v_and_b32_e32 v152, 0xffffc000, v66
	v_add3_u32 v66, 0, v152, v74
	ds_read2st64_b32 v[148:149], v66 offset1:4
	ds_read2st64_b32 v[150:151], v66 offset0:8 offset1:12
	ds_read2st64_b32 v[108:109], v66 offset0:16 offset1:20
	ds_read2st64_b32 v[106:107], v66 offset0:24 offset1:28
	ds_read2st64_b32 v[104:105], v66 offset0:32 offset1:36
	ds_read2st64_b32 v[102:103], v66 offset0:40 offset1:44
	ds_read2st64_b32 v[100:101], v66 offset0:48 offset1:52
	ds_read2st64_b32 v[98:99], v66 offset0:56 offset1:60
	ds_read2st64_b32 v[96:97], v66 offset0:64 offset1:68
	ds_read2st64_b32 v[94:95], v66 offset0:72 offset1:76
	ds_read2st64_b32 v[92:93], v66 offset0:80 offset1:84
	ds_read2st64_b32 v[90:91], v66 offset0:88 offset1:92
	ds_read2st64_b32 v[88:89], v66 offset0:96 offset1:100
	ds_read2st64_b32 v[86:87], v66 offset0:104 offset1:108
	ds_read2st64_b32 v[84:85], v66 offset0:112 offset1:116
	ds_read2st64_b32 v[82:83], v66 offset0:120 offset1:124
	ds_read2st64_b32 v[80:81], v66 offset0:128 offset1:132
	ds_read2st64_b32 v[78:79], v66 offset0:136 offset1:140
	ds_read2st64_b32 v[76:77], v66 offset0:144 offset1:148
	ds_read2st64_b32 v[72:73], v66 offset0:152 offset1:156
	ds_read2st64_b32 v[70:71], v66 offset0:160 offset1:164
	ds_read2st64_b32 v[68:69], v66 offset0:168 offset1:172
	ds_read2st64_b32 v[66:67], v66 offset0:176 offset1:180
	v_add3_u32 v74, s34, v152, v74
	v_readlane_b32 s9, v239, 6
	v_readlane_b32 s10, v239, 7
	v_readlane_b32 s11, v239, 8
	v_readlane_b32 s12, v239, 9
	v_readlane_b32 s13, v239, 10
	v_readlane_b32 s14, v239, 11
	v_readlane_b32 s15, v239, 12
	v_readlane_b32 s4, v239, 49
	v_readlane_b32 s5, v239, 50
	v_readlane_b32 s6, v239, 51
	v_readlane_b32 s7, v239, 52
	v_readlane_b32 s10, v239, 55
	v_readlane_b32 s11, v239, 56
	s_add_i32 s41, s41, s42
	s_add_i32 s40, s40, s68
	s_add_i32 s3, s3, s26
	s_cmpk_lt_i32 s40, 0x410
	v_readlane_b32 s8, v239, 53
	v_readlane_b32 s9, v239, 54
	v_readlane_b32 s12, v239, 57
	v_readlane_b32 s13, v239, 58
	v_readlane_b32 s14, v239, 59
	v_readlane_b32 s15, v239, 60
	v_readlane_b32 s16, v239, 61
	v_readlane_b32 s17, v239, 62
	v_readlane_b32 s18, v239, 63
	v_readlane_b32 s19, v238, 0
	s_waitcnt vmcnt(19) lgkmcnt(14)
	v_fma_f32 v148, v128, v148, v124
	v_fmac_f32_e32 v148, v127, v149
	v_fma_f32 v149, v128, v149, v124
	v_fmac_f32_e32 v149, v127, v150
	v_fmac_f32_e32 v148, v126, v150
	v_fmac_f32_e32 v149, v126, v151
	v_fmac_f32_e32 v148, v125, v151
	v_fmac_f32_e32 v149, v125, v108
	v_fmac_f32_e32 v148, v123, v108
	v_fmac_f32_e32 v149, v123, v109
	v_fmac_f32_e32 v148, v122, v109
	v_fmac_f32_e32 v149, v122, v106
	v_fmac_f32_e32 v148, v120, v106
	v_fmac_f32_e32 v149, v120, v107
	v_fmac_f32_e32 v148, v118, v107
	v_fmac_f32_e32 v149, v118, v104
	v_fmac_f32_e32 v148, v121, v104
	v_fmac_f32_e32 v149, v121, v105
	v_fmac_f32_e32 v148, v119, v105
	v_fmac_f32_e32 v149, v119, v102
	v_fmac_f32_e32 v148, v117, v102
	v_fmac_f32_e32 v149, v117, v103
	v_fmac_f32_e32 v148, v116, v103
	v_fmac_f32_e32 v149, v116, v100
	s_waitcnt vmcnt(18)
	v_fmac_f32_e32 v148, v147, v100
	v_fmac_f32_e32 v149, v147, v101
	s_waitcnt vmcnt(17)
	v_fmac_f32_e32 v148, v146, v101
	v_fmac_f32_e32 v149, v146, v98
	s_waitcnt vmcnt(16)
	v_fmac_f32_e32 v148, v144, v98
	v_fmac_f32_e32 v149, v144, v99
	s_waitcnt vmcnt(15)
	v_fmac_f32_e32 v148, v142, v99
	v_fmac_f32_e32 v149, v142, v96
	s_waitcnt vmcnt(14)
	v_fmac_f32_e32 v148, v140, v96
	v_fmac_f32_e32 v149, v140, v97
	s_waitcnt vmcnt(13)
	v_fmac_f32_e32 v148, v138, v97
	s_waitcnt lgkmcnt(13)
	v_fmac_f32_e32 v149, v138, v94
	s_waitcnt vmcnt(12)
	v_fmac_f32_e32 v148, v136, v94
	v_fmac_f32_e32 v149, v136, v95
	s_waitcnt vmcnt(11)
	v_fmac_f32_e32 v148, v133, v95
	s_waitcnt lgkmcnt(12)
	v_fmac_f32_e32 v149, v133, v92
	s_waitcnt vmcnt(10)
	v_fmac_f32_e32 v148, v145, v92
	v_fmac_f32_e32 v149, v145, v93
	s_waitcnt vmcnt(9)
	v_fmac_f32_e32 v148, v143, v93
	s_waitcnt lgkmcnt(11)
	v_fmac_f32_e32 v149, v143, v90
	s_waitcnt vmcnt(8)
	v_fmac_f32_e32 v148, v141, v90
	v_fmac_f32_e32 v149, v141, v91
	s_waitcnt vmcnt(7)
	v_fmac_f32_e32 v148, v139, v91
	s_waitcnt lgkmcnt(10)
	v_fmac_f32_e32 v149, v139, v88
	s_waitcnt vmcnt(6)
	v_fmac_f32_e32 v148, v137, v88
	v_fmac_f32_e32 v149, v137, v89
	s_waitcnt vmcnt(5)
	v_fmac_f32_e32 v148, v134, v89
	s_waitcnt lgkmcnt(9)
	v_fmac_f32_e32 v149, v134, v86
	s_waitcnt vmcnt(4)
	v_fmac_f32_e32 v148, v131, v86
	v_fmac_f32_e32 v149, v131, v87
	s_waitcnt vmcnt(3)
	v_fmac_f32_e32 v148, v129, v87
	s_waitcnt lgkmcnt(8)
	v_fmac_f32_e32 v149, v129, v84
	s_waitcnt vmcnt(2)
	v_fmac_f32_e32 v148, v135, v84
	v_fmac_f32_e32 v149, v135, v85
	s_waitcnt vmcnt(1)
	v_fmac_f32_e32 v148, v132, v85
	s_waitcnt lgkmcnt(7)
	v_fmac_f32_e32 v149, v132, v82
	s_waitcnt vmcnt(0)
	v_fmac_f32_e32 v148, v130, v82
	v_fmac_f32_e32 v149, v130, v83
	ds_write2st64_b32 v74, v148, v149 offset1:4
	v_fma_f32 v148, v128, v150, v124
	v_fmac_f32_e32 v148, v127, v151
	v_fma_f32 v149, v128, v151, v124
	v_fmac_f32_e32 v148, v126, v108
	v_fmac_f32_e32 v149, v127, v108
	v_fma_f32 v108, v128, v108, v124
	v_fmac_f32_e32 v148, v125, v109
	v_fmac_f32_e32 v149, v126, v109
	v_fmac_f32_e32 v108, v127, v109
	v_fma_f32 v109, v128, v109, v124
	v_fmac_f32_e32 v148, v123, v106
	v_fmac_f32_e32 v149, v125, v106
	v_fmac_f32_e32 v108, v126, v106
	v_fmac_f32_e32 v109, v127, v106
	v_fma_f32 v106, v128, v106, v124
	v_fmac_f32_e32 v148, v122, v107
	v_fmac_f32_e32 v149, v123, v107
	v_fmac_f32_e32 v108, v125, v107
	v_fmac_f32_e32 v109, v126, v107
	v_fmac_f32_e32 v106, v127, v107
	v_fma_f32 v107, v128, v107, v124
	v_fmac_f32_e32 v148, v120, v104
	v_fmac_f32_e32 v149, v122, v104
	v_fmac_f32_e32 v108, v123, v104
	v_fmac_f32_e32 v109, v125, v104
	v_fmac_f32_e32 v106, v126, v104
	v_fmac_f32_e32 v107, v127, v104
	v_fma_f32 v104, v128, v104, v124
	v_fmac_f32_e32 v148, v118, v105
	v_fmac_f32_e32 v149, v120, v105
	v_fmac_f32_e32 v108, v122, v105
	v_fmac_f32_e32 v109, v123, v105
	v_fmac_f32_e32 v106, v125, v105
	v_fmac_f32_e32 v107, v126, v105
	v_fmac_f32_e32 v104, v127, v105
	v_fma_f32 v105, v128, v105, v124
	v_fmac_f32_e32 v148, v121, v102
	v_fmac_f32_e32 v149, v118, v102
	v_fmac_f32_e32 v108, v120, v102
	v_fmac_f32_e32 v109, v122, v102
	v_fmac_f32_e32 v106, v123, v102
	v_fmac_f32_e32 v107, v125, v102
	v_fmac_f32_e32 v104, v126, v102
	v_fmac_f32_e32 v105, v127, v102
	v_fma_f32 v102, v128, v102, v124
	v_fmac_f32_e32 v148, v119, v103
	v_fmac_f32_e32 v149, v121, v103
	v_fmac_f32_e32 v108, v118, v103
	v_fmac_f32_e32 v109, v120, v103
	v_fmac_f32_e32 v106, v122, v103
	v_fmac_f32_e32 v107, v123, v103
	v_fmac_f32_e32 v104, v125, v103
	v_fmac_f32_e32 v105, v126, v103
	v_fmac_f32_e32 v102, v127, v103
	v_fma_f32 v103, v128, v103, v124
	v_fmac_f32_e32 v148, v117, v100
	v_fmac_f32_e32 v149, v119, v100
	v_fmac_f32_e32 v108, v121, v100
	v_fmac_f32_e32 v109, v118, v100
	v_fmac_f32_e32 v106, v120, v100
	v_fmac_f32_e32 v107, v122, v100
	v_fmac_f32_e32 v104, v123, v100
	v_fmac_f32_e32 v105, v125, v100
	v_fmac_f32_e32 v102, v126, v100
	v_fmac_f32_e32 v103, v127, v100
	v_fma_f32 v100, v128, v100, v124
	v_fmac_f32_e32 v148, v116, v101
	v_fmac_f32_e32 v149, v117, v101
	v_fmac_f32_e32 v108, v119, v101
	v_fmac_f32_e32 v109, v121, v101
	v_fmac_f32_e32 v106, v118, v101
	v_fmac_f32_e32 v107, v120, v101
	v_fmac_f32_e32 v104, v122, v101
	v_fmac_f32_e32 v105, v123, v101
	v_fmac_f32_e32 v102, v125, v101
	v_fmac_f32_e32 v103, v126, v101
	v_fmac_f32_e32 v100, v127, v101
	v_fma_f32 v101, v128, v101, v124
	v_fmac_f32_e32 v148, v147, v98
	v_fmac_f32_e32 v149, v116, v98
	v_fmac_f32_e32 v108, v117, v98
	v_fmac_f32_e32 v109, v119, v98
	v_fmac_f32_e32 v106, v121, v98
	v_fmac_f32_e32 v107, v118, v98
	v_fmac_f32_e32 v104, v120, v98
	v_fmac_f32_e32 v105, v122, v98
	v_fmac_f32_e32 v102, v123, v98
	v_fmac_f32_e32 v103, v125, v98
	v_fmac_f32_e32 v100, v126, v98
	v_fmac_f32_e32 v101, v127, v98
	v_fma_f32 v98, v128, v98, v124
	v_fmac_f32_e32 v124, v128, v99
	v_fmac_f32_e32 v98, v127, v99
	v_fmac_f32_e32 v124, v127, v96
	v_fmac_f32_e32 v101, v126, v99
	v_fmac_f32_e32 v98, v126, v96
	v_fmac_f32_e32 v124, v126, v97
	v_fmac_f32_e32 v100, v125, v99
	v_fmac_f32_e32 v101, v125, v96
	v_fmac_f32_e32 v98, v125, v97
	v_fmac_f32_e32 v124, v125, v94
	v_fmac_f32_e32 v103, v123, v99
	v_fmac_f32_e32 v100, v123, v96
	v_fmac_f32_e32 v101, v123, v97
	v_fmac_f32_e32 v98, v123, v94
	v_fmac_f32_e32 v124, v123, v95
	v_fmac_f32_e32 v102, v122, v99
	v_fmac_f32_e32 v103, v122, v96
	v_fmac_f32_e32 v100, v122, v97
	v_fmac_f32_e32 v101, v122, v94
	v_fmac_f32_e32 v98, v122, v95
	v_fmac_f32_e32 v124, v122, v92
	v_fmac_f32_e32 v105, v120, v99
	v_fmac_f32_e32 v102, v120, v96
	v_fmac_f32_e32 v103, v120, v97
	v_fmac_f32_e32 v100, v120, v94
	v_fmac_f32_e32 v101, v120, v95
	v_fmac_f32_e32 v98, v120, v92
	v_fmac_f32_e32 v124, v120, v93
	v_fmac_f32_e32 v104, v118, v99
	v_fmac_f32_e32 v105, v118, v96
	v_fmac_f32_e32 v102, v118, v97
	v_fmac_f32_e32 v103, v118, v94
	v_fmac_f32_e32 v100, v118, v95
	v_fmac_f32_e32 v101, v118, v92
	v_fmac_f32_e32 v98, v118, v93
	v_fmac_f32_e32 v124, v118, v90
	v_fmac_f32_e32 v107, v121, v99
	v_fmac_f32_e32 v104, v121, v96
	v_fmac_f32_e32 v105, v121, v97
	v_fmac_f32_e32 v102, v121, v94
	v_fmac_f32_e32 v103, v121, v95
	v_fmac_f32_e32 v100, v121, v92
	v_fmac_f32_e32 v101, v121, v93
	v_fmac_f32_e32 v98, v121, v90
	v_fmac_f32_e32 v124, v121, v91
	v_fmac_f32_e32 v106, v119, v99
	v_fmac_f32_e32 v107, v119, v96
	v_fmac_f32_e32 v104, v119, v97
	v_fmac_f32_e32 v105, v119, v94
	v_fmac_f32_e32 v102, v119, v95
	v_fmac_f32_e32 v103, v119, v92
	v_fmac_f32_e32 v100, v119, v93
	v_fmac_f32_e32 v101, v119, v90
	v_fmac_f32_e32 v98, v119, v91
	v_fmac_f32_e32 v124, v119, v88
	v_fmac_f32_e32 v109, v117, v99
	v_fmac_f32_e32 v106, v117, v96
	v_fmac_f32_e32 v107, v117, v97
	v_fmac_f32_e32 v104, v117, v94
	v_fmac_f32_e32 v105, v117, v95
	v_fmac_f32_e32 v102, v117, v92
	v_fmac_f32_e32 v103, v117, v93
	v_fmac_f32_e32 v100, v117, v90
	v_fmac_f32_e32 v101, v117, v91
	v_fmac_f32_e32 v98, v117, v88
	v_fmac_f32_e32 v124, v117, v89
	v_fmac_f32_e32 v108, v116, v99
	v_fmac_f32_e32 v109, v116, v96
	v_fmac_f32_e32 v106, v116, v97
	v_fmac_f32_e32 v107, v116, v94
	v_fmac_f32_e32 v104, v116, v95
	v_fmac_f32_e32 v105, v116, v92
	v_fmac_f32_e32 v102, v116, v93
	v_fmac_f32_e32 v103, v116, v90
	v_fmac_f32_e32 v100, v116, v91
	v_fmac_f32_e32 v101, v116, v88
	v_fmac_f32_e32 v98, v116, v89
	v_fmac_f32_e32 v124, v116, v86
	v_fmac_f32_e32 v149, v147, v99
	v_fmac_f32_e32 v108, v147, v96
	v_fmac_f32_e32 v109, v147, v97
	v_fmac_f32_e32 v106, v147, v94
	v_fmac_f32_e32 v107, v147, v95
	v_fmac_f32_e32 v104, v147, v92
	v_fmac_f32_e32 v105, v147, v93
	v_fmac_f32_e32 v102, v147, v90
	v_fmac_f32_e32 v103, v147, v91
	v_fmac_f32_e32 v100, v147, v88
	v_fmac_f32_e32 v101, v147, v89
	v_fmac_f32_e32 v98, v147, v86
	v_fmac_f32_e32 v124, v147, v87
	v_fmac_f32_e32 v148, v146, v99
	v_fmac_f32_e32 v149, v146, v96
	v_fmac_f32_e32 v108, v146, v97
	v_fmac_f32_e32 v109, v146, v94
	v_fmac_f32_e32 v106, v146, v95
	v_fmac_f32_e32 v107, v146, v92
	v_fmac_f32_e32 v104, v146, v93
	v_fmac_f32_e32 v105, v146, v90
	v_fmac_f32_e32 v102, v146, v91
	v_fmac_f32_e32 v103, v146, v88
	v_fmac_f32_e32 v100, v146, v89
	v_fmac_f32_e32 v101, v146, v86
	v_fmac_f32_e32 v98, v146, v87
	v_fmac_f32_e32 v124, v146, v84
	v_fmac_f32_e32 v148, v144, v96
	v_fmac_f32_e32 v149, v144, v97
	v_fmac_f32_e32 v108, v144, v94
	v_fmac_f32_e32 v109, v144, v95
	v_fmac_f32_e32 v106, v144, v92
	v_fmac_f32_e32 v107, v144, v93
	v_fmac_f32_e32 v104, v144, v90
	v_fmac_f32_e32 v105, v144, v91
	v_fmac_f32_e32 v102, v144, v88
	v_fmac_f32_e32 v103, v144, v89
	v_fmac_f32_e32 v100, v144, v86
	v_fmac_f32_e32 v101, v144, v87
	v_fmac_f32_e32 v98, v144, v84
	v_fmac_f32_e32 v124, v144, v85
	v_fmac_f32_e32 v148, v142, v97
	v_fmac_f32_e32 v149, v142, v94
	v_fmac_f32_e32 v108, v142, v95
	v_fmac_f32_e32 v109, v142, v92
	v_fmac_f32_e32 v106, v142, v93
	v_fmac_f32_e32 v107, v142, v90
	v_fmac_f32_e32 v104, v142, v91
	v_fmac_f32_e32 v105, v142, v88
	v_fmac_f32_e32 v102, v142, v89
	v_fmac_f32_e32 v103, v142, v86
	v_fmac_f32_e32 v100, v142, v87
	v_fmac_f32_e32 v101, v142, v84
	v_fmac_f32_e32 v98, v142, v85
	v_fmac_f32_e32 v124, v142, v82
	v_fmac_f32_e32 v148, v140, v94
	v_fmac_f32_e32 v149, v140, v95
	v_fmac_f32_e32 v108, v140, v92
	v_fmac_f32_e32 v109, v140, v93
	v_fmac_f32_e32 v106, v140, v90
	v_fmac_f32_e32 v107, v140, v91
	v_fmac_f32_e32 v104, v140, v88
	v_fmac_f32_e32 v105, v140, v89
	v_fmac_f32_e32 v102, v140, v86
	v_fmac_f32_e32 v103, v140, v87
	v_fmac_f32_e32 v100, v140, v84
	v_fmac_f32_e32 v101, v140, v85
	v_fmac_f32_e32 v98, v140, v82
	v_fmac_f32_e32 v124, v140, v83
	v_fmac_f32_e32 v148, v138, v95
	v_fmac_f32_e32 v149, v138, v92
	v_fmac_f32_e32 v108, v138, v93
	v_fmac_f32_e32 v109, v138, v90
	v_fmac_f32_e32 v106, v138, v91
	v_fmac_f32_e32 v107, v138, v88
	v_fmac_f32_e32 v104, v138, v89
	v_fmac_f32_e32 v105, v138, v86
	v_fmac_f32_e32 v102, v138, v87
	v_fmac_f32_e32 v103, v138, v84
	v_fmac_f32_e32 v100, v138, v85
	v_fmac_f32_e32 v101, v138, v82
	v_fmac_f32_e32 v98, v138, v83
	s_waitcnt lgkmcnt(7)
	v_fmac_f32_e32 v124, v138, v80
	v_fmac_f32_e32 v148, v136, v92
	v_fmac_f32_e32 v149, v136, v93
	v_fmac_f32_e32 v108, v136, v90
	v_fmac_f32_e32 v109, v136, v91
	v_fmac_f32_e32 v106, v136, v88
	v_fmac_f32_e32 v107, v136, v89
	v_fmac_f32_e32 v104, v136, v86
	v_fmac_f32_e32 v105, v136, v87
	v_fmac_f32_e32 v102, v136, v84
	v_fmac_f32_e32 v103, v136, v85
	v_fmac_f32_e32 v100, v136, v82
	v_fmac_f32_e32 v101, v136, v83
	v_fmac_f32_e32 v98, v136, v80
	v_fmac_f32_e32 v124, v136, v81
	v_fmac_f32_e32 v148, v133, v93
	v_fmac_f32_e32 v149, v133, v90
	v_fmac_f32_e32 v108, v133, v91
	v_fmac_f32_e32 v109, v133, v88
	v_fmac_f32_e32 v106, v133, v89
	v_fmac_f32_e32 v107, v133, v86
	v_fmac_f32_e32 v104, v133, v87
	v_fmac_f32_e32 v105, v133, v84
	v_fmac_f32_e32 v102, v133, v85
	v_fmac_f32_e32 v103, v133, v82
	v_fmac_f32_e32 v100, v133, v83
	v_fmac_f32_e32 v101, v133, v80
	v_fmac_f32_e32 v98, v133, v81
	s_waitcnt lgkmcnt(6)
	v_fmac_f32_e32 v124, v133, v78
	v_fmac_f32_e32 v148, v145, v90
	v_fmac_f32_e32 v149, v145, v91
	v_fmac_f32_e32 v108, v145, v88
	v_fmac_f32_e32 v109, v145, v89
	v_fmac_f32_e32 v106, v145, v86
	v_fmac_f32_e32 v107, v145, v87
	v_fmac_f32_e32 v104, v145, v84
	v_fmac_f32_e32 v105, v145, v85
	v_fmac_f32_e32 v102, v145, v82
	v_fmac_f32_e32 v103, v145, v83
	v_fmac_f32_e32 v100, v145, v80
	v_fmac_f32_e32 v101, v145, v81
	v_fmac_f32_e32 v98, v145, v78
	v_fmac_f32_e32 v124, v145, v79
	v_fmac_f32_e32 v148, v143, v91
	v_fmac_f32_e32 v149, v143, v88
	v_fmac_f32_e32 v108, v143, v89
	v_fmac_f32_e32 v109, v143, v86
	v_fmac_f32_e32 v106, v143, v87
	v_fmac_f32_e32 v107, v143, v84
	v_fmac_f32_e32 v104, v143, v85
	v_fmac_f32_e32 v105, v143, v82
	v_fmac_f32_e32 v102, v143, v83
	v_fmac_f32_e32 v103, v143, v80
	v_fmac_f32_e32 v100, v143, v81
	v_fmac_f32_e32 v101, v143, v78
	v_fmac_f32_e32 v98, v143, v79
	s_waitcnt lgkmcnt(5)
	v_fmac_f32_e32 v124, v143, v76
	v_fmac_f32_e32 v148, v141, v88
	v_fmac_f32_e32 v149, v141, v89
	v_fmac_f32_e32 v108, v141, v86
	v_fmac_f32_e32 v109, v141, v87
	v_fmac_f32_e32 v106, v141, v84
	v_fmac_f32_e32 v107, v141, v85
	v_fmac_f32_e32 v104, v141, v82
	v_fmac_f32_e32 v105, v141, v83
	v_fmac_f32_e32 v102, v141, v80
	v_fmac_f32_e32 v103, v141, v81
	v_fmac_f32_e32 v100, v141, v78
	v_fmac_f32_e32 v101, v141, v79
	v_fmac_f32_e32 v98, v141, v76
	v_fmac_f32_e32 v124, v141, v77
	v_fmac_f32_e32 v148, v139, v89
	v_fmac_f32_e32 v149, v139, v86
	v_fmac_f32_e32 v108, v139, v87
	v_fmac_f32_e32 v109, v139, v84
	v_fmac_f32_e32 v106, v139, v85
	v_fmac_f32_e32 v107, v139, v82
	v_fmac_f32_e32 v104, v139, v83
	v_fmac_f32_e32 v105, v139, v80
	v_fmac_f32_e32 v102, v139, v81
	v_fmac_f32_e32 v103, v139, v78
	v_fmac_f32_e32 v100, v139, v79
	v_fmac_f32_e32 v101, v139, v76
	v_fmac_f32_e32 v98, v139, v77
	s_waitcnt lgkmcnt(4)
	v_fmac_f32_e32 v124, v139, v72
	v_fmac_f32_e32 v148, v137, v86
	v_fmac_f32_e32 v149, v137, v87
	v_fmac_f32_e32 v108, v137, v84
	v_fmac_f32_e32 v109, v137, v85
	v_fmac_f32_e32 v106, v137, v82
	v_fmac_f32_e32 v107, v137, v83
	v_fmac_f32_e32 v104, v137, v80
	v_fmac_f32_e32 v105, v137, v81
	v_fmac_f32_e32 v102, v137, v78
	v_fmac_f32_e32 v103, v137, v79
	v_fmac_f32_e32 v100, v137, v76
	v_fmac_f32_e32 v101, v137, v77
	v_fmac_f32_e32 v98, v137, v72
	v_fmac_f32_e32 v124, v137, v73
	v_fmac_f32_e32 v148, v134, v87
	v_fmac_f32_e32 v149, v134, v84
	v_fmac_f32_e32 v108, v134, v85
	v_fmac_f32_e32 v109, v134, v82
	v_fmac_f32_e32 v106, v134, v83
	v_fmac_f32_e32 v107, v134, v80
	v_fmac_f32_e32 v104, v134, v81
	v_fmac_f32_e32 v105, v134, v78
	v_fmac_f32_e32 v102, v134, v79
	v_fmac_f32_e32 v103, v134, v76
	v_fmac_f32_e32 v100, v134, v77
	v_fmac_f32_e32 v101, v134, v72
	v_fmac_f32_e32 v98, v134, v73
	s_waitcnt lgkmcnt(3)
	v_fmac_f32_e32 v124, v134, v70
	v_fmac_f32_e32 v148, v131, v84
	v_fmac_f32_e32 v149, v131, v85
	v_fmac_f32_e32 v108, v131, v82
	v_fmac_f32_e32 v109, v131, v83
	v_fmac_f32_e32 v106, v131, v80
	v_fmac_f32_e32 v107, v131, v81
	v_fmac_f32_e32 v104, v131, v78
	v_fmac_f32_e32 v105, v131, v79
	v_fmac_f32_e32 v102, v131, v76
	v_fmac_f32_e32 v103, v131, v77
	v_fmac_f32_e32 v100, v131, v72
	v_fmac_f32_e32 v101, v131, v73
	v_fmac_f32_e32 v98, v131, v70
	v_fmac_f32_e32 v124, v131, v71
	v_fmac_f32_e32 v148, v129, v85
	v_fmac_f32_e32 v149, v129, v82
	v_fmac_f32_e32 v108, v129, v83
	v_fmac_f32_e32 v109, v129, v80
	v_fmac_f32_e32 v106, v129, v81
	v_fmac_f32_e32 v107, v129, v78
	v_fmac_f32_e32 v104, v129, v79
	v_fmac_f32_e32 v105, v129, v76
	v_fmac_f32_e32 v102, v129, v77
	v_fmac_f32_e32 v103, v129, v72
	v_fmac_f32_e32 v100, v129, v73
	v_fmac_f32_e32 v101, v129, v70
	v_fmac_f32_e32 v98, v129, v71
	s_waitcnt lgkmcnt(2)
	v_fmac_f32_e32 v124, v129, v68
	v_fmac_f32_e32 v148, v135, v82
	v_fmac_f32_e32 v149, v135, v83
	v_fmac_f32_e32 v108, v135, v80
	v_fmac_f32_e32 v109, v135, v81
	v_fmac_f32_e32 v106, v135, v78
	v_fmac_f32_e32 v107, v135, v79
	v_fmac_f32_e32 v104, v135, v76
	v_fmac_f32_e32 v105, v135, v77
	v_fmac_f32_e32 v102, v135, v72
	v_fmac_f32_e32 v103, v135, v73
	v_fmac_f32_e32 v100, v135, v70
	v_fmac_f32_e32 v101, v135, v71
	v_fmac_f32_e32 v98, v135, v68
	v_fmac_f32_e32 v124, v135, v69
	v_fmac_f32_e32 v148, v132, v83
	v_fmac_f32_e32 v149, v132, v80
	v_fmac_f32_e32 v108, v132, v81
	v_fmac_f32_e32 v109, v132, v78
	v_fmac_f32_e32 v106, v132, v79
	v_fmac_f32_e32 v107, v132, v76
	v_fmac_f32_e32 v104, v132, v77
	v_fmac_f32_e32 v105, v132, v72
	v_fmac_f32_e32 v102, v132, v73
	v_fmac_f32_e32 v103, v132, v70
	v_fmac_f32_e32 v100, v132, v71
	v_fmac_f32_e32 v101, v132, v68
	v_fmac_f32_e32 v98, v132, v69
	s_waitcnt lgkmcnt(1)
	v_fmac_f32_e32 v124, v132, v66
	v_fmac_f32_e32 v148, v130, v80
	v_fmac_f32_e32 v149, v130, v81
	v_fmac_f32_e32 v108, v130, v78
	v_fmac_f32_e32 v109, v130, v79
	v_fmac_f32_e32 v106, v130, v76
	v_fmac_f32_e32 v107, v130, v77
	v_fmac_f32_e32 v104, v130, v72
	v_fmac_f32_e32 v105, v130, v73
	v_fmac_f32_e32 v102, v130, v70
	v_fmac_f32_e32 v103, v130, v71
	v_fmac_f32_e32 v100, v130, v68
	v_fmac_f32_e32 v101, v130, v69
	v_fmac_f32_e32 v98, v130, v66
	v_fmac_f32_e32 v124, v130, v67
	ds_write2st64_b32 v74, v148, v149 offset0:8 offset1:12
	ds_write2st64_b32 v74, v108, v109 offset0:16 offset1:20
	ds_write2st64_b32 v74, v106, v107 offset0:24 offset1:28
	ds_write2st64_b32 v74, v104, v105 offset0:32 offset1:36
	ds_write2st64_b32 v74, v102, v103 offset0:40 offset1:44
	ds_write2st64_b32 v74, v100, v101 offset0:48 offset1:52
	ds_write2st64_b32 v74, v98, v124 offset0:56 offset1:60
	v_lshlrev_b32_e32 v74, 2, v115
	v_add_u32_e32 v86, s34, v74
	v_lshl_add_u32 v88, v113, 12, v86
	s_waitcnt lgkmcnt(0)
	s_barrier
	global_load_dwordx4 v[66:69], v74, s[4:5]
	global_load_dwordx4 v[70:73], v74, s[6:7]
	ds_read_b128 v[78:81], v88
	v_and_b32_e32 v74, 64, v110
	v_add_u32_e32 v74, 64, v74
	v_xor_b32_e32 v76, 1, v110
	v_cmp_lt_i32_e32 vcc, v76, v74
	s_waitcnt lgkmcnt(0)
	v_mov_b32_e32 v77, v80
	v_mov_b32_e32 v82, v78
	v_cndmask_b32_e32 v76, v110, v76, vcc
	v_lshlrev_b32_e32 v89, 2, v76
	v_mov_b32_e32 v76, v79
	v_mov_b32_e32 v83, v81
	v_pk_add_f32 v[76:77], v[76:77], v[82:83]
	v_xor_b32_e32 v82, 2, v110
	v_add_f32_e32 v76, v76, v77
	v_cmp_lt_i32_e32 vcc, v82, v74
	v_lshl_or_b32 v87, v113, 2, 1
	s_waitcnt lgkmcnt(0)
	s_nop 1
	v_add_f32_dpp v76, v76, v76 quad_perm:[1,0,3,2] row_mask:0xf bank_mask:0xf
	v_cndmask_b32_e32 v82, v110, v82, vcc
	v_lshlrev_b32_e32 v90, 2, v82
	v_xor_b32_e32 v82, 4, v110
	v_cmp_lt_i32_e32 vcc, v82, v74
	s_waitcnt lgkmcnt(0)
	s_nop 1
	v_add_f32_dpp v76, v76, v76 quad_perm:[2,3,0,1] row_mask:0xf bank_mask:0xf
	v_cndmask_b32_e32 v82, v110, v82, vcc
	v_lshlrev_b32_e32 v91, 2, v82
	v_xor_b32_e32 v82, 8, v110
	v_cmp_lt_i32_e32 vcc, v82, v74
	s_waitcnt lgkmcnt(0)
	s_nop 1
	v_add_f32_dpp v76, v76, v76 row_half_mirror row_mask:0xf bank_mask:0xf
	v_cndmask_b32_e32 v82, v110, v82, vcc
	v_lshlrev_b32_e32 v92, 2, v82
	v_xor_b32_e32 v82, 16, v110
	v_cmp_lt_i32_e32 vcc, v82, v74
	s_waitcnt lgkmcnt(0)
	s_nop 1
	v_add_f32_dpp v76, v76, v76 row_mirror row_mask:0xf bank_mask:0xf
	v_cndmask_b32_e32 v82, v110, v82, vcc
	v_lshlrev_b32_e32 v93, 2, v82
	v_xor_b32_e32 v82, 32, v110
	v_cmp_lt_i32_e32 vcc, v82, v74
	s_nop 1
	v_cndmask_b32_e32 v74, v110, v82, vcc
	v_lshlrev_b32_e32 v94, 2, v74
	s_waitcnt lgkmcnt(0)
	v_mov_b32_e32 v77, v76
	v_mov_b32_e32 v254, v76
	s_nop 1
	v_permlane16_swap_b32 v77, v254
	v_add_f32_e32 v74, v77, v254
	s_waitcnt lgkmcnt(0)
	v_mov_b32_e32 v76, v74
	v_mov_b32_e32 v254, v74
	s_nop 1
	v_permlane32_swap_b32 v76, v254
	v_add_f32_e32 v74, v76, v254
	v_fmamk_f32 v83, v74, 0xbb800000, v79
	v_fmamk_f32 v82, v74, 0xbb800000, v78
	v_fmamk_f32 v81, v74, 0xbb800000, v81
	v_fmac_f32_e32 v80, 0xbb800000, v74
	v_pk_mul_f32 v[76:77], v[80:81], v[80:81]
	v_pk_mul_f32 v[78:79], v[82:83], v[82:83]
	s_nop 0
	v_pk_mov_b32 v[84:85], v[78:79], v[76:77] op_sel:[1,0]
	v_mov_b32_e32 v79, v77
	v_pk_add_f32 v[76:77], v[84:85], v[78:79]
	s_waitcnt vmcnt(0)
	v_mov_b32_e32 v78, v70
	v_add_f32_e32 v74, v76, v77
	v_mov_b32_e32 v77, v80
	v_mov_b32_e32 v79, v72
	v_mov_b32_e32 v80, v83
	v_mov_b32_e32 v72, v71
	s_waitcnt lgkmcnt(0)
	s_nop 1
	v_add_f32_dpp v74, v74, v74 quad_perm:[1,0,3,2] row_mask:0xf bank_mask:0xf
	s_waitcnt lgkmcnt(0)
	s_nop 1
	v_add_f32_dpp v74, v74, v74 quad_perm:[2,3,0,1] row_mask:0xf bank_mask:0xf
	s_waitcnt lgkmcnt(0)
	s_nop 1
	v_add_f32_dpp v74, v74, v74 row_half_mirror row_mask:0xf bank_mask:0xf
	s_waitcnt lgkmcnt(0)
	s_nop 1
	v_add_f32_dpp v74, v74, v74 row_mirror row_mask:0xf bank_mask:0xf
	s_waitcnt lgkmcnt(0)
	v_mov_b32_e32 v76, v74
	v_mov_b32_e32 v254, v74
	s_nop 1
	v_permlane16_swap_b32 v76, v254
	v_add_f32_e32 v74, v76, v254
	s_waitcnt lgkmcnt(0)
	v_mov_b32_e32 v76, v74
	v_mov_b32_e32 v254, v74
	s_nop 1
	v_permlane32_swap_b32 v76, v254
	v_add_f32_e32 v74, v76, v254
	v_fmamk_f32 v74, v74, 0x3b800000, v111
	v_mul_f32_e32 v76, 0x4b800000, v74
	v_cmp_gt_f32_e32 vcc, s36, v74
	s_nop 1
	v_cndmask_b32_e32 v74, v74, v76, vcc
	v_rsq_f32_e32 v74, v74
	s_nop 0
	v_mul_f32_e32 v76, 0x45800000, v74
	v_cndmask_b32_e32 v74, v74, v76, vcc
	v_mov_b32_e32 v76, v82
	v_pk_mul_f32 v[84:85], v[76:77], v[74:75] op_sel_hi:[1,0]
	v_mov_b32_e32 v76, v66
	v_mov_b32_e32 v77, v68
	v_pk_fma_f32 v[84:85], v[76:77], v[84:85], v[78:79]
	v_pk_mul_f32 v[80:81], v[80:81], v[74:75] op_sel_hi:[1,0]
	v_mul_f32_e32 v66, 0xbfb8aa3b, v84
	v_mov_b32_e32 v68, v67
	v_exp_f32_e32 v70, v66
	v_pk_fma_f32 v[66:67], v[68:69], v[80:81], v[72:73]
	v_mul_f32_e32 v74, 0xbfb8aa3b, v85
	v_mul_f32_e32 v71, 0xbfb8aa3b, v66
	v_exp_f32_e32 v71, v71
	v_exp_f32_e32 v74, v74
	v_mul_f32_e32 v80, 0xbfb8aa3b, v67
	v_exp_f32_e32 v81, v80
	v_add_f32_e32 v71, 1.0, v71
	v_add_f32_e32 v70, 1.0, v70
	v_rcp_f32_e32 v80, v71
	v_add_f32_e32 v71, 1.0, v74
	v_rcp_f32_e32 v70, v70
	v_rcp_f32_e32 v71, v71
	v_add_f32_e32 v74, 1.0, v81
	v_rcp_f32_e32 v81, v74
	v_lshl_add_u32 v74, v115, 1, s35
	v_pk_mul_f32 v[70:71], v[84:85], v[70:71]
	v_pk_mul_f32 v[66:67], v[66:67], v[80:81]
	v_and_b32_sdwa v80, v71, v112 dst_sel:DWORD dst_unused:UNUSED_PAD src0_sel:WORD_1 src1_sel:DWORD
	v_and_b32_sdwa v81, v70, v112 dst_sel:DWORD dst_unused:UNUSED_PAD src0_sel:WORD_1 src1_sel:DWORD
	v_add3_u32 v70, v70, v81, s37
	v_add3_u32 v71, v71, v80, s37
	v_and_b32_sdwa v80, v67, v112 dst_sel:DWORD dst_unused:UNUSED_PAD src0_sel:WORD_1 src1_sel:DWORD
	v_and_b32_sdwa v81, v66, v112 dst_sel:DWORD dst_unused:UNUSED_PAD src0_sel:WORD_1 src1_sel:DWORD
	v_add3_u32 v67, v67, v80, s37
	v_add3_u32 v66, v66, v81, s37
	v_and_b32_e32 v67, 0xffff0000, v67
	v_and_b32_e32 v66, 0xffff0000, v66
	v_or_b32_sdwa v67, v67, v71 dst_sel:DWORD dst_unused:UNUSED_PAD src0_sel:DWORD src1_sel:WORD_1
	v_or_b32_sdwa v66, v66, v70 dst_sel:DWORD dst_unused:UNUSED_PAD src0_sel:DWORD src1_sel:WORD_1
	v_mad_u64_u32 v[70:71], s[4:5], v113, s38, v[74:75]
	ds_write_b64 v70, v[66:67]
	v_lshl_add_u32 v66, v87, 10, v86
	ds_read_b128 v[80:83], v66
	s_waitcnt lgkmcnt(0)
	v_mov_b32_e32 v66, v81
	v_mov_b32_e32 v67, v82
	v_mov_b32_e32 v70, v80
	v_mov_b32_e32 v71, v83
	v_pk_add_f32 v[66:67], v[66:67], v[70:71]
	s_nop 0
	v_add_f32_e32 v66, v66, v67
	s_waitcnt lgkmcnt(0)
	s_nop 1
	v_add_f32_dpp v66, v66, v66 quad_perm:[1,0,3,2] row_mask:0xf bank_mask:0xf
	s_waitcnt lgkmcnt(0)
	s_nop 1
	v_add_f32_dpp v66, v66, v66 quad_perm:[2,3,0,1] row_mask:0xf bank_mask:0xf
	s_waitcnt lgkmcnt(0)
	s_nop 1
	v_add_f32_dpp v66, v66, v66 row_half_mirror row_mask:0xf bank_mask:0xf
	s_waitcnt lgkmcnt(0)
	s_nop 1
	v_add_f32_dpp v66, v66, v66 row_mirror row_mask:0xf bank_mask:0xf
	s_waitcnt lgkmcnt(0)
	v_mov_b32_e32 v67, v66
	v_mov_b32_e32 v254, v66
	s_nop 1
	v_permlane16_swap_b32 v67, v254
	v_add_f32_e32 v66, v67, v254
	s_waitcnt lgkmcnt(0)
	v_mov_b32_e32 v67, v66
	v_mov_b32_e32 v254, v66
	s_nop 1
	v_permlane32_swap_b32 v67, v254
	v_add_f32_e32 v70, v67, v254
	v_fmamk_f32 v67, v70, 0xbb800000, v81
	v_fmamk_f32 v66, v70, 0xbb800000, v80
	v_fmamk_f32 v83, v70, 0xbb800000, v83
	v_fmac_f32_e32 v82, 0xbb800000, v70
	v_pk_mul_f32 v[70:71], v[82:83], v[82:83]
	v_pk_mul_f32 v[80:81], v[66:67], v[66:67]
	s_nop 0
	v_pk_mov_b32 v[84:85], v[80:81], v[70:71] op_sel:[1,0]
	v_mov_b32_e32 v81, v71
	v_pk_add_f32 v[70:71], v[84:85], v[80:81]
	v_mov_b32_e32 v80, v66
	v_add_f32_e32 v70, v70, v71
	v_mov_b32_e32 v81, v82
	v_mov_b32_e32 v82, v67
	s_waitcnt lgkmcnt(0)
	s_nop 1
	v_add_f32_dpp v70, v70, v70 quad_perm:[1,0,3,2] row_mask:0xf bank_mask:0xf
	s_waitcnt lgkmcnt(0)
	s_nop 1
	v_add_f32_dpp v70, v70, v70 quad_perm:[2,3,0,1] row_mask:0xf bank_mask:0xf
	s_waitcnt lgkmcnt(0)
	s_nop 1
	v_add_f32_dpp v70, v70, v70 row_half_mirror row_mask:0xf bank_mask:0xf
	s_waitcnt lgkmcnt(0)
	s_nop 1
	v_add_f32_dpp v70, v70, v70 row_mirror row_mask:0xf bank_mask:0xf
	s_waitcnt lgkmcnt(0)
	v_mov_b32_e32 v71, v70
	v_mov_b32_e32 v254, v70
	s_nop 1
	v_permlane16_swap_b32 v71, v254
	v_add_f32_e32 v70, v71, v254
	s_waitcnt lgkmcnt(0)
	v_mov_b32_e32 v71, v70
	v_mov_b32_e32 v254, v70
	s_nop 1
	v_permlane32_swap_b32 v71, v254
	v_add_f32_e32 v70, v71, v254
	v_fmamk_f32 v70, v70, 0x3b800000, v111
	v_mul_f32_e32 v71, 0x4b800000, v70
	v_cmp_gt_f32_e32 vcc, s36, v70
	s_nop 1
	v_cndmask_b32_e32 v70, v70, v71, vcc
	v_rsq_f32_e32 v70, v70
	s_nop 0
	v_mul_f32_e32 v71, 0x45800000, v70
	v_cndmask_b32_e32 v70, v70, v71, vcc
	v_pk_mul_f32 v[80:81], v[80:81], v[70:71] op_sel_hi:[1,0]
	s_nop 0
	v_pk_fma_f32 v[80:81], v[76:77], v[80:81], v[78:79]
	s_nop 0
	v_mul_f32_e32 v66, 0xbfb8aa3b, v80
	v_exp_f32_e32 v71, v66
	s_nop 0
	v_pk_mul_f32 v[66:67], v[82:83], v[70:71] op_sel_hi:[1,0]
	s_nop 0
	v_pk_fma_f32 v[66:67], v[68:69], v[66:67], v[72:73]
	s_nop 0
	v_mul_f32_e32 v70, 0xbfb8aa3b, v66
	v_exp_f32_e32 v82, v70
	v_add_f32_e32 v70, 1.0, v71
	v_rcp_f32_e32 v70, v70
	v_add_f32_e32 v71, 1.0, v82
	v_mul_f32_e32 v82, 0xbfb8aa3b, v81
	v_exp_f32_e32 v83, v82
	v_mul_f32_e32 v82, 0xbfb8aa3b, v67
	v_exp_f32_e32 v84, v82
	v_rcp_f32_e32 v82, v71
	v_add_f32_e32 v71, 1.0, v83
	v_rcp_f32_e32 v71, v71
	v_add_f32_e32 v83, 1.0, v84
	v_rcp_f32_e32 v83, v83
	v_pk_mul_f32 v[70:71], v[80:81], v[70:71]
	s_nop 0
	v_and_b32_sdwa v80, v71, v112 dst_sel:DWORD dst_unused:UNUSED_PAD src0_sel:WORD_1 src1_sel:DWORD
	v_pk_mul_f32 v[66:67], v[66:67], v[82:83]
	v_and_b32_sdwa v81, v70, v112 dst_sel:DWORD dst_unused:UNUSED_PAD src0_sel:WORD_1 src1_sel:DWORD
	v_add3_u32 v70, v70, v81, s37
	v_add3_u32 v71, v71, v80, s37
	v_and_b32_sdwa v80, v67, v112 dst_sel:DWORD dst_unused:UNUSED_PAD src0_sel:WORD_1 src1_sel:DWORD
	v_and_b32_sdwa v81, v66, v112 dst_sel:DWORD dst_unused:UNUSED_PAD src0_sel:WORD_1 src1_sel:DWORD
	v_add3_u32 v67, v67, v80, s37
	v_add3_u32 v66, v66, v81, s37
	v_and_b32_e32 v67, 0xffff0000, v67
	v_and_b32_e32 v66, 0xffff0000, v66
	v_or_b32_sdwa v67, v67, v71 dst_sel:DWORD dst_unused:UNUSED_PAD src0_sel:DWORD src1_sel:WORD_1
	v_or_b32_sdwa v66, v66, v70 dst_sel:DWORD dst_unused:UNUSED_PAD src0_sel:DWORD src1_sel:WORD_1
	v_mad_u64_u32 v[70:71], s[4:5], v87, s39, v[74:75]
	ds_write_b64 v70, v[66:67]
	ds_read_b128 v[80:83], v88 offset:2048
	s_waitcnt lgkmcnt(0)
	v_mov_b32_e32 v66, v81
	v_mov_b32_e32 v67, v82
	v_mov_b32_e32 v84, v80
	v_mov_b32_e32 v85, v83
	v_pk_add_f32 v[66:67], v[66:67], v[84:85]
	s_nop 0
	v_add_f32_e32 v66, v66, v67
	s_waitcnt lgkmcnt(0)
	s_nop 1
	v_add_f32_dpp v66, v66, v66 quad_perm:[1,0,3,2] row_mask:0xf bank_mask:0xf
	s_waitcnt lgkmcnt(0)
	s_nop 1
	v_add_f32_dpp v66, v66, v66 quad_perm:[2,3,0,1] row_mask:0xf bank_mask:0xf
	s_waitcnt lgkmcnt(0)
	s_nop 1
	v_add_f32_dpp v66, v66, v66 row_half_mirror row_mask:0xf bank_mask:0xf
	s_waitcnt lgkmcnt(0)
	s_nop 1
	v_add_f32_dpp v66, v66, v66 row_mirror row_mask:0xf bank_mask:0xf
	s_waitcnt lgkmcnt(0)
	v_mov_b32_e32 v67, v66
	v_mov_b32_e32 v254, v66
	s_nop 1
	v_permlane16_swap_b32 v67, v254
	v_add_f32_e32 v66, v67, v254
	s_waitcnt lgkmcnt(0)
	v_mov_b32_e32 v67, v66
	v_mov_b32_e32 v254, v66
	s_nop 1
	v_permlane32_swap_b32 v67, v254
	v_add_f32_e32 v71, v67, v254
	v_fmamk_f32 v67, v71, 0xbb800000, v81
	v_fmamk_f32 v66, v71, 0xbb800000, v80
	v_fmamk_f32 v83, v71, 0xbb800000, v83
	v_fmac_f32_e32 v82, 0xbb800000, v71
	v_pk_mul_f32 v[80:81], v[82:83], v[82:83]
	v_pk_mul_f32 v[84:85], v[66:67], v[66:67]
	s_nop 0
	v_pk_mov_b32 v[86:87], v[84:85], v[80:81] op_sel:[1,0]
	v_mov_b32_e32 v85, v81
	v_pk_add_f32 v[80:81], v[86:87], v[84:85]
	s_nop 0
	v_add_f32_e32 v71, v80, v81
	v_mov_b32_e32 v80, v66
	v_mov_b32_e32 v81, v82
	v_mov_b32_e32 v82, v67
	s_waitcnt lgkmcnt(0)
	s_nop 1
	v_add_f32_dpp v71, v71, v71 quad_perm:[1,0,3,2] row_mask:0xf bank_mask:0xf
	s_waitcnt lgkmcnt(0)
	s_nop 1
	v_add_f32_dpp v71, v71, v71 quad_perm:[2,3,0,1] row_mask:0xf bank_mask:0xf
	s_waitcnt lgkmcnt(0)
	s_nop 1
	v_add_f32_dpp v71, v71, v71 row_half_mirror row_mask:0xf bank_mask:0xf
	s_waitcnt lgkmcnt(0)
	s_nop 1
	v_add_f32_dpp v71, v71, v71 row_mirror row_mask:0xf bank_mask:0xf
	s_waitcnt lgkmcnt(0)
	v_mov_b32_e32 v74, v71
	v_mov_b32_e32 v254, v71
	s_nop 1
	v_permlane16_swap_b32 v74, v254
	v_add_f32_e32 v71, v74, v254
	s_waitcnt lgkmcnt(0)
	v_mov_b32_e32 v74, v71
	v_mov_b32_e32 v254, v71
	s_nop 1
	v_permlane32_swap_b32 v74, v254
	v_add_f32_e32 v71, v74, v254
	v_fmamk_f32 v71, v71, 0x3b800000, v111
	v_mul_f32_e32 v74, 0x4b800000, v71
	v_cmp_gt_f32_e32 vcc, s36, v71
	s_nop 1
	v_cndmask_b32_e32 v71, v71, v74, vcc
	v_rsq_f32_e32 v71, v71
	s_nop 0
	v_mul_f32_e32 v74, 0x45800000, v71
	v_cndmask_b32_e32 v74, v71, v74, vcc
	v_pk_mul_f32 v[80:81], v[80:81], v[74:75] op_sel_hi:[1,0]
	s_nop 0
	v_pk_fma_f32 v[80:81], v[76:77], v[80:81], v[78:79]
	s_nop 0
	v_mul_f32_e32 v66, 0xbfb8aa3b, v80
	v_exp_f32_e32 v71, v66
	v_pk_mul_f32 v[66:67], v[82:83], v[74:75] op_sel_hi:[1,0]
	v_add_f32_e32 v71, 1.0, v71
	v_pk_fma_f32 v[66:67], v[68:69], v[66:67], v[72:73]
	v_rcp_f32_e32 v82, v71
	v_mul_f32_e32 v74, 0xbfb8aa3b, v66
	v_exp_f32_e32 v74, v74
	v_mul_f32_e32 v83, 0xbfb8aa3b, v67
	v_exp_f32_e32 v85, v83
	v_add_f32_e32 v71, 1.0, v74
	v_mul_f32_e32 v74, 0xbfb8aa3b, v81
	v_exp_f32_e32 v74, v74
	v_rcp_f32_e32 v84, v71
	v_add_f32_e32 v71, 1.0, v74
	v_rcp_f32_e32 v83, v71
	v_add_f32_e32 v71, 1.0, v85
	v_rcp_f32_e32 v85, v71
	v_pk_mul_f32 v[80:81], v[80:81], v[82:83]
	s_nop 0
	v_and_b32_sdwa v71, v81, v112 dst_sel:DWORD dst_unused:UNUSED_PAD src0_sel:WORD_1 src1_sel:DWORD
	v_pk_mul_f32 v[66:67], v[66:67], v[84:85]
	v_and_b32_sdwa v74, v80, v112 dst_sel:DWORD dst_unused:UNUSED_PAD src0_sel:WORD_1 src1_sel:DWORD
	v_add3_u32 v74, v80, v74, s37
	v_add3_u32 v71, v81, v71, s37
	v_and_b32_sdwa v80, v67, v112 dst_sel:DWORD dst_unused:UNUSED_PAD src0_sel:WORD_1 src1_sel:DWORD
	v_and_b32_sdwa v81, v66, v112 dst_sel:DWORD dst_unused:UNUSED_PAD src0_sel:WORD_1 src1_sel:DWORD
	v_add3_u32 v67, v67, v80, s37
	v_add3_u32 v66, v66, v81, s37
	v_and_b32_e32 v67, 0xffff0000, v67
	v_and_b32_e32 v66, 0xffff0000, v66
	v_or_b32_sdwa v67, v67, v71 dst_sel:DWORD dst_unused:UNUSED_PAD src0_sel:DWORD src1_sel:WORD_1
	v_or_b32_sdwa v66, v66, v74 dst_sel:DWORD dst_unused:UNUSED_PAD src0_sel:DWORD src1_sel:WORD_1
	ds_write_b64 v70, v[66:67] offset:528
	ds_read_b128 v[80:83], v88 offset:3072
	s_waitcnt lgkmcnt(0)
	v_mov_b32_e32 v66, v81
	v_mov_b32_e32 v67, v82
	v_mov_b32_e32 v84, v80
	v_mov_b32_e32 v85, v83
	v_pk_add_f32 v[66:67], v[66:67], v[84:85]
	s_nop 0
	v_add_f32_e32 v66, v66, v67
	s_waitcnt lgkmcnt(0)
	s_nop 1
	v_add_f32_dpp v66, v66, v66 quad_perm:[1,0,3,2] row_mask:0xf bank_mask:0xf
	s_waitcnt lgkmcnt(0)
	s_nop 1
	v_add_f32_dpp v66, v66, v66 quad_perm:[2,3,0,1] row_mask:0xf bank_mask:0xf
	s_waitcnt lgkmcnt(0)
	s_nop 1
	v_add_f32_dpp v66, v66, v66 row_half_mirror row_mask:0xf bank_mask:0xf
	s_waitcnt lgkmcnt(0)
	s_nop 1
	v_add_f32_dpp v66, v66, v66 row_mirror row_mask:0xf bank_mask:0xf
	s_waitcnt lgkmcnt(0)
	v_mov_b32_e32 v67, v66
	v_mov_b32_e32 v254, v66
	s_nop 1
	v_permlane16_swap_b32 v67, v254
	v_add_f32_e32 v66, v67, v254
	s_waitcnt lgkmcnt(0)
	v_mov_b32_e32 v67, v66
	v_mov_b32_e32 v254, v66
	s_nop 1
	v_permlane32_swap_b32 v67, v254
	v_add_f32_e32 v71, v67, v254
	v_fmamk_f32 v67, v71, 0xbb800000, v81
	v_fmamk_f32 v66, v71, 0xbb800000, v80
	v_fmamk_f32 v83, v71, 0xbb800000, v83
	v_fmac_f32_e32 v82, 0xbb800000, v71
	v_pk_mul_f32 v[80:81], v[82:83], v[82:83]
	v_pk_mul_f32 v[84:85], v[66:67], v[66:67]
	s_nop 0
	v_pk_mov_b32 v[86:87], v[84:85], v[80:81] op_sel:[1,0]
	v_mov_b32_e32 v85, v81
	v_pk_add_f32 v[80:81], v[86:87], v[84:85]
	s_nop 0
	v_add_f32_e32 v71, v80, v81
	v_mov_b32_e32 v80, v66
	v_mov_b32_e32 v81, v82
	v_mov_b32_e32 v82, v67
	s_waitcnt lgkmcnt(0)
	s_nop 1
	v_add_f32_dpp v71, v71, v71 quad_perm:[1,0,3,2] row_mask:0xf bank_mask:0xf
	s_waitcnt lgkmcnt(0)
	s_nop 1
	v_add_f32_dpp v71, v71, v71 quad_perm:[2,3,0,1] row_mask:0xf bank_mask:0xf
	s_waitcnt lgkmcnt(0)
	s_nop 1
	v_add_f32_dpp v71, v71, v71 row_half_mirror row_mask:0xf bank_mask:0xf
	s_waitcnt lgkmcnt(0)
	s_nop 1
	v_add_f32_dpp v71, v71, v71 row_mirror row_mask:0xf bank_mask:0xf
	s_waitcnt lgkmcnt(0)
	v_mov_b32_e32 v74, v71
	v_mov_b32_e32 v254, v71
	s_nop 1
	v_permlane16_swap_b32 v74, v254
	v_add_f32_e32 v71, v74, v254
	s_waitcnt lgkmcnt(0)
	v_mov_b32_e32 v74, v71
	v_mov_b32_e32 v254, v71
	s_nop 1
	v_permlane32_swap_b32 v74, v254
	v_add_f32_e32 v71, v74, v254
	v_fmamk_f32 v71, v71, 0x3b800000, v111
	v_mul_f32_e32 v74, 0x4b800000, v71
	v_cmp_gt_f32_e32 vcc, s36, v71
	s_nop 1
	v_cndmask_b32_e32 v71, v71, v74, vcc
	v_rsq_f32_e32 v71, v71
	s_nop 0
	v_mul_f32_e32 v74, 0x45800000, v71
	v_cndmask_b32_e32 v74, v71, v74, vcc
	v_pk_mul_f32 v[80:81], v[80:81], v[74:75] op_sel_hi:[1,0]
	s_nop 0
	v_pk_fma_f32 v[76:77], v[76:77], v[80:81], v[78:79]
	s_nop 0
	v_mul_f32_e32 v66, 0xbfb8aa3b, v76
	v_exp_f32_e32 v71, v66
	v_pk_mul_f32 v[66:67], v[82:83], v[74:75] op_sel_hi:[1,0]
	v_and_b32_e32 v74, 15, v114
	v_pk_fma_f32 v[66:67], v[68:69], v[66:67], v[72:73]
	s_nop 0
	v_mul_f32_e32 v68, 0xbfb8aa3b, v66
	v_exp_f32_e32 v69, v68
	v_add_f32_e32 v68, 1.0, v71
	v_mul_f32_e32 v71, 0xbfb8aa3b, v77
	v_exp_f32_e32 v71, v71
	v_mul_f32_e32 v72, 0xbfb8aa3b, v67
	v_exp_f32_e32 v73, v72
	v_add_f32_e32 v69, 1.0, v69
	v_rcp_f32_e32 v72, v69
	v_add_f32_e32 v69, 1.0, v71
	v_rcp_f32_e32 v68, v68
	v_rcp_f32_e32 v69, v69
	v_add_f32_e32 v71, 1.0, v73
	v_rcp_f32_e32 v73, v71
	v_pk_mul_f32 v[68:69], v[76:77], v[68:69]
	s_nop 0
	v_and_b32_sdwa v71, v69, v112 dst_sel:DWORD dst_unused:UNUSED_PAD src0_sel:WORD_1 src1_sel:DWORD
	v_pk_mul_f32 v[66:67], v[66:67], v[72:73]
	v_and_b32_sdwa v72, v68, v112 dst_sel:DWORD dst_unused:UNUSED_PAD src0_sel:WORD_1 src1_sel:DWORD
	v_add3_u32 v68, v68, v72, s37
	v_add3_u32 v69, v69, v71, s37
	v_and_b32_sdwa v71, v67, v112 dst_sel:DWORD dst_unused:UNUSED_PAD src0_sel:WORD_1 src1_sel:DWORD
	v_and_b32_sdwa v72, v66, v112 dst_sel:DWORD dst_unused:UNUSED_PAD src0_sel:WORD_1 src1_sel:DWORD
	v_add3_u32 v67, v67, v71, s37
	v_add3_u32 v66, v66, v72, s37
	v_and_b32_e32 v67, 0xffff0000, v67
	v_and_b32_e32 v66, 0xffff0000, v66
	v_or_b32_sdwa v67, v67, v69 dst_sel:DWORD dst_unused:UNUSED_PAD src0_sel:DWORD src1_sel:WORD_1
	v_or_b32_sdwa v66, v66, v68 dst_sel:DWORD dst_unused:UNUSED_PAD src0_sel:DWORD src1_sel:WORD_1
	ds_write_b64 v70, v[66:67] offset:1056
	v_and_b32_e32 v66, 48, v114
	v_mul_u32_u24_e32 v67, 0x210, v74
	v_add3_u32 v100, s35, v66, v67
	s_waitcnt lgkmcnt(0)
	s_barrier
	ds_read_b128 v[66:69], v100
	ds_read_b128 v[70:73], v100 offset:64
	ds_read_b128 v[80:83], v100 offset:8448
	ds_read_b128 v[84:87], v100 offset:8512
	s_waitcnt lgkmcnt(3)
	v_mfma_f32_16x16x32_bf16 v[76:79], v[2:5], v[66:69], 0
	s_waitcnt lgkmcnt(1)
	v_mfma_f32_16x16x32_bf16 v[88:91], v[2:5], v[80:83], 0
	v_mfma_f32_16x16x32_bf16 v[66:69], v[34:37], v[66:69], 0
	v_mfma_f32_16x16x32_bf16 v[80:83], v[34:37], v[80:83], 0
	v_mfma_f32_16x16x32_bf16 v[76:79], v[6:9], v[70:73], v[76:79]
	s_waitcnt lgkmcnt(0)
	v_mfma_f32_16x16x32_bf16 v[88:91], v[6:9], v[84:87], v[88:91]
	v_mfma_f32_16x16x32_bf16 v[66:69], v[38:41], v[70:73], v[66:69]
	v_mfma_f32_16x16x32_bf16 v[70:73], v[38:41], v[84:87], v[80:83]
	s_nop 2
	ds_read_b128 v[80:83], v100 offset:128
	ds_read_b128 v[84:87], v100 offset:192
	ds_read_b128 v[92:95], v100 offset:8576
	ds_read_b128 v[96:99], v100 offset:8640
	s_waitcnt lgkmcnt(3)
	v_mfma_f32_16x16x32_bf16 v[76:79], v[10:13], v[80:83], v[76:79]
	s_waitcnt lgkmcnt(1)
	v_mfma_f32_16x16x32_bf16 v[88:91], v[10:13], v[92:95], v[88:91]
	v_mfma_f32_16x16x32_bf16 v[66:69], v[42:45], v[80:83], v[66:69]
	v_mfma_f32_16x16x32_bf16 v[70:73], v[42:45], v[92:95], v[70:73]
	v_mfma_f32_16x16x32_bf16 v[76:79], v[14:17], v[84:87], v[76:79]
	s_waitcnt lgkmcnt(0)
	v_mfma_f32_16x16x32_bf16 v[80:83], v[14:17], v[96:99], v[88:91]
	v_mfma_f32_16x16x32_bf16 v[66:69], v[46:49], v[84:87], v[66:69]
	ds_read_b128 v[84:87], v100 offset:256
	s_nop 0
	ds_read_b128 v[88:91], v100 offset:320
	v_mfma_f32_16x16x32_bf16 v[70:73], v[46:49], v[96:99], v[70:73]
	ds_read_b128 v[92:95], v100 offset:8704
	ds_read_b128 v[96:99], v100 offset:8768
	s_waitcnt lgkmcnt(3)
	v_mfma_f32_16x16x32_bf16 v[76:79], v[18:21], v[84:87], v[76:79]
	v_mfma_f32_16x16x32_bf16 v[66:69], v[50:53], v[84:87], v[66:69]
	s_waitcnt lgkmcnt(1)
	v_mfma_f32_16x16x32_bf16 v[80:83], v[18:21], v[92:95], v[80:83]
	v_mfma_f32_16x16x32_bf16 v[70:73], v[50:53], v[92:95], v[70:73]
	v_mfma_f32_16x16x32_bf16 v[76:79], v[22:25], v[88:91], v[76:79]
	v_mfma_f32_16x16x32_bf16 v[66:69], v[54:57], v[88:91], v[66:69]
	ds_read_b128 v[84:87], v100 offset:384
	ds_read_b128 v[88:91], v100 offset:448
	s_waitcnt lgkmcnt(2)
	v_mfma_f32_16x16x32_bf16 v[80:83], v[22:25], v[96:99], v[80:83]
	v_mfma_f32_16x16x32_bf16 v[70:73], v[54:57], v[96:99], v[70:73]
	ds_read_b128 v[92:95], v100 offset:8832
	ds_read_b128 v[96:99], v100 offset:8896
	s_waitcnt lgkmcnt(3)
	v_mfma_f32_16x16x32_bf16 v[76:79], v[26:29], v[84:87], v[76:79]
	v_mfma_f32_16x16x32_bf16 v[66:69], v[58:61], v[84:87], v[66:69]
	v_lshrrev_b32_e32 v84, 2, v114
	v_and_b32_e32 v84, 12, v84
	s_waitcnt lgkmcnt(1)
	v_mfma_f32_16x16x32_bf16 v[80:83], v[26:29], v[92:95], v[80:83]
	v_mfma_f32_16x16x32_bf16 v[70:73], v[58:61], v[92:95], v[70:73]
	v_lshl_or_b32 v92, v113, 5, v84
	v_ashrrev_i32_e32 v93, 31, v92
	v_lshl_add_u64 v[94:95], v[92:93], 2, s[10:11]
	v_mfma_f32_16x16x32_bf16 v[76:79], v[30:33], v[88:91], v[76:79]
	v_mfma_f32_16x16x32_bf16 v[66:69], v[62:65], v[88:91], v[66:69]
	v_or_b32_e32 v88, s41, v74
	s_nop 4
	v_pk_add_f32 v[78:79], v[78:79], v[184:185]
	v_pk_add_f32 v[76:77], v[76:77], v[182:183]
	v_and_b32_sdwa v74, v78, v112 dst_sel:DWORD dst_unused:UNUSED_PAD src0_sel:WORD_1 src1_sel:DWORD
	v_and_b32_sdwa v89, v76, v112 dst_sel:DWORD dst_unused:UNUSED_PAD src0_sel:WORD_1 src1_sel:DWORD
	v_add3_u32 v76, v76, v89, s37
	v_add3_u32 v74, v78, v74, s37
	v_and_b32_sdwa v78, v79, v112 dst_sel:DWORD dst_unused:UNUSED_PAD src0_sel:WORD_1 src1_sel:DWORD
	v_and_b32_sdwa v89, v77, v112 dst_sel:DWORD dst_unused:UNUSED_PAD src0_sel:WORD_1 src1_sel:DWORD
	v_add3_u32 v78, v79, v78, s37
	v_add3_u32 v77, v77, v89, s37
	s_waitcnt lgkmcnt(0)
	v_mfma_f32_16x16x32_bf16 v[80:83], v[30:33], v[96:99], v[80:83]
	v_and_b32_e32 v78, 0xffff0000, v78
	v_and_b32_e32 v79, 0xffff0000, v77
	v_ashrrev_i32_e32 v89, 31, v88
	v_or_b32_sdwa v77, v78, v74 dst_sel:DWORD dst_unused:UNUSED_PAD src0_sel:DWORD src1_sel:WORD_1
	v_or_b32_sdwa v76, v79, v76 dst_sel:DWORD dst_unused:UNUSED_PAD src0_sel:DWORD src1_sel:WORD_1
	v_lshlrev_b64 v[78:79], 11, v[88:89]
	v_lshl_add_u64 v[78:79], s[88:89], 0, v[78:79]
	v_lshl_add_u64 v[90:91], v[78:79], 0, s[0:1]
	v_lshlrev_b64 v[78:79], 1, v[92:93]
	v_lshl_add_u64 v[100:101], v[90:91], 0, v[78:79]
	v_pk_add_f32 v[82:83], v[82:83], v[184:185]
	v_pk_add_f32 v[80:81], v[80:81], v[182:183]
	global_store_dwordx2 v[100:101], v[76:77], off
	v_and_b32_sdwa v74, v82, v112 dst_sel:DWORD dst_unused:UNUSED_PAD src0_sel:WORD_1 src1_sel:DWORD
	v_and_b32_sdwa v77, v80, v112 dst_sel:DWORD dst_unused:UNUSED_PAD src0_sel:WORD_1 src1_sel:DWORD
	v_add3_u32 v77, v80, v77, s37
	v_add3_u32 v74, v82, v74, s37
	v_and_b32_sdwa v80, v83, v112 dst_sel:DWORD dst_unused:UNUSED_PAD src0_sel:WORD_1 src1_sel:DWORD
	v_and_b32_sdwa v82, v81, v112 dst_sel:DWORD dst_unused:UNUSED_PAD src0_sel:WORD_1 src1_sel:DWORD
	v_add3_u32 v80, v83, v80, s37
	v_add3_u32 v81, v81, v82, s37
	v_or_b32_e32 v76, 16, v88
	v_and_b32_e32 v80, 0xffff0000, v80
	v_and_b32_e32 v82, 0xffff0000, v81
	v_or_b32_sdwa v81, v80, v74 dst_sel:DWORD dst_unused:UNUSED_PAD src0_sel:DWORD src1_sel:WORD_1
	v_or_b32_sdwa v80, v82, v77 dst_sel:DWORD dst_unused:UNUSED_PAD src0_sel:DWORD src1_sel:WORD_1
	v_ashrrev_i32_e32 v77, 31, v76
	v_lshlrev_b64 v[76:77], 11, v[76:77]
	v_lshl_add_u64 v[76:77], s[88:89], 0, v[76:77]
	v_lshl_add_u64 v[82:83], v[76:77], 0, s[0:1]
	v_lshl_add_u64 v[76:77], v[82:83], 0, v[78:79]
	global_store_dwordx2 v[76:77], v[80:81], off
	v_mfma_f32_16x16x32_bf16 v[70:73], v[62:65], v[96:99], v[70:73]
	v_or_b32_e32 v80, 16, v92
	v_ashrrev_i32_e32 v81, 31, v80
	v_pk_add_f32 v[68:69], v[68:69], v[188:189]
	v_pk_add_f32 v[66:67], v[66:67], v[186:187]
	v_and_b32_sdwa v74, v68, v112 dst_sel:DWORD dst_unused:UNUSED_PAD src0_sel:WORD_1 src1_sel:DWORD
	v_and_b32_sdwa v84, v66, v112 dst_sel:DWORD dst_unused:UNUSED_PAD src0_sel:WORD_1 src1_sel:DWORD
	v_add3_u32 v68, v68, v74, s37
	v_and_b32_sdwa v74, v69, v112 dst_sel:DWORD dst_unused:UNUSED_PAD src0_sel:WORD_1 src1_sel:DWORD
	v_add3_u32 v66, v66, v84, s37
	v_and_b32_sdwa v84, v67, v112 dst_sel:DWORD dst_unused:UNUSED_PAD src0_sel:WORD_1 src1_sel:DWORD
	v_add3_u32 v69, v69, v74, s37
	v_add3_u32 v67, v67, v84, s37
	v_and_b32_e32 v69, 0xffff0000, v69
	v_and_b32_e32 v74, 0xffff0000, v67
	v_or_b32_sdwa v67, v69, v68 dst_sel:DWORD dst_unused:UNUSED_PAD src0_sel:DWORD src1_sel:WORD_1
	v_lshlrev_b64 v[68:69], 1, v[80:81]
	v_or_b32_sdwa v66, v74, v66 dst_sel:DWORD dst_unused:UNUSED_PAD src0_sel:DWORD src1_sel:WORD_1
	v_lshl_add_u64 v[80:81], v[90:91], 0, v[68:69]
	global_store_dwordx2 v[80:81], v[66:67], off
	v_pk_add_f32 v[66:67], v[72:73], v[188:189]
	v_pk_add_f32 v[70:71], v[70:71], v[186:187]
	v_and_b32_sdwa v72, v66, v112 dst_sel:DWORD dst_unused:UNUSED_PAD src0_sel:WORD_1 src1_sel:DWORD
	v_and_b32_sdwa v73, v70, v112 dst_sel:DWORD dst_unused:UNUSED_PAD src0_sel:WORD_1 src1_sel:DWORD
	v_add3_u32 v70, v70, v73, s37
	v_add3_u32 v66, v66, v72, s37
	v_and_b32_sdwa v72, v67, v112 dst_sel:DWORD dst_unused:UNUSED_PAD src0_sel:WORD_1 src1_sel:DWORD
	v_and_b32_sdwa v73, v71, v112 dst_sel:DWORD dst_unused:UNUSED_PAD src0_sel:WORD_1 src1_sel:DWORD
	v_add3_u32 v67, v67, v72, s37
	v_add3_u32 v71, v71, v73, s37
	v_and_b32_e32 v67, 0xffff0000, v67
	v_and_b32_e32 v71, 0xffff0000, v71
	v_or_b32_sdwa v67, v67, v66 dst_sel:DWORD dst_unused:UNUSED_PAD src0_sel:DWORD src1_sel:WORD_1
	v_or_b32_sdwa v66, v71, v70 dst_sel:DWORD dst_unused:UNUSED_PAD src0_sel:DWORD src1_sel:WORD_1
	v_lshl_add_u64 v[68:69], v[82:83], 0, v[68:69]
	global_store_dwordx2 v[68:69], v[66:67], off
	s_barrier
	s_cbranch_scc0 .LBB0_755

.LBB0_1962:
	s_cmpk_gt_i32 s96, 0x3ff
	s_barrier
	s_cbranch_scc1 .LBB0_1997
	v_and_b32_e32 v2, 15, v108
	v_lshl_or_b32 v34, s3, 5, v2
	v_and_b32_e32 v74, 48, v108
	v_mov_b32_e32 v75, 0
	v_lshl_add_u64 v[2:3], s[88:89], 0, v[74:75]
	s_mov_b64 s[0:1], 0x420000
	v_ashrrev_i32_e32 v35, 31, v34
	v_lshl_add_u64 v[36:37], v[2:3], 0, s[0:1]
	v_lshlrev_b64 v[2:3], 9, v[34:35]
	v_or_b32_e32 v34, 16, v34
	v_ashrrev_i32_e32 v35, 31, v34
	v_lshlrev_b64 v[34:35], 9, v[34:35]
	v_lshl_add_u64 v[38:39], v[36:37], 0, v[2:3]
	v_lshl_add_u64 v[66:67], v[36:37], 0, v[34:35]
	global_load_dwordx4 v[2:5], v[38:39], off
	global_load_dwordx4 v[6:9], v[38:39], off offset:64
	global_load_dwordx4 v[10:13], v[38:39], off offset:128
	global_load_dwordx4 v[14:17], v[38:39], off offset:192
	global_load_dwordx4 v[18:21], v[38:39], off offset:256
	global_load_dwordx4 v[22:25], v[38:39], off offset:320
	global_load_dwordx4 v[26:29], v[38:39], off offset:384
	global_load_dwordx4 v[30:33], v[38:39], off offset:448
	global_load_dwordx4 v[34:37], v[66:67], off
	s_nop 0
	global_load_dwordx4 v[38:41], v[66:67], off offset:64
	global_load_dwordx4 v[42:45], v[66:67], off offset:128
	global_load_dwordx4 v[46:49], v[66:67], off offset:192
	global_load_dwordx4 v[50:53], v[66:67], off offset:256
	global_load_dwordx4 v[54:57], v[66:67], off offset:320
	global_load_dwordx4 v[58:61], v[66:67], off offset:384
	global_load_dwordx4 v[62:65], v[66:67], off offset:448
	v_readlane_b32 s0, v239, 1
	v_readlane_b32 s12, v239, 13
	v_readlane_b32 s1, v239, 2
	v_readlane_b32 s3, v239, 4
	v_readlane_b32 s13, v239, 14
	s_add_u32 s0, s12, 0x7c00
	s_addc_u32 s1, s13, 0
	s_lshl_b32 s3, s96, 5
	s_lshl_b32 s28, s68, 5
	s_movk_i32 s29, 0xf80
	s_movk_i32 s30, 0x4000
	s_movk_i32 s31, 0x1640
	s_movk_i32 s33, 0xd80
	s_movk_i32 s34, 0xb80
	s_movk_i32 s35, 0x980
	s_movk_i32 s36, 0x780
	s_movk_i32 s37, 0x580
	s_movk_i32 s38, 0x380
	s_movk_i32 s39, 0x180
	s_add_i32 s40, 0, 0x10000
	s_add_i32 s41, 0, 0x18000
	v_mov_b32_e32 v111, 0x3727c5ac
	s_mov_b32 s42, 0x800000
	s_movk_i32 s43, 0x7fff
	s_movk_i32 s44, 0x840
	s_movk_i32 s45, 0x210
	s_mov_b64 s[24:25], 0x5a00600
	v_mov_b32_e32 v112, 1
	s_mov_b32 s46, s96
	v_readlane_b32 s2, v239, 3
	v_readlane_b32 s4, v239, 5
	v_readlane_b32 s5, v239, 6
	v_readlane_b32 s6, v239, 7
	v_readlane_b32 s7, v239, 8
	v_readlane_b32 s8, v239, 9
	v_readlane_b32 s9, v239, 10
	v_readlane_b32 s10, v239, 11
	v_readlane_b32 s11, v239, 12
	v_readlane_b32 s14, v239, 15
	v_readlane_b32 s15, v239, 16
	v_readlane_b32 s100, v239, 55
	v_readlane_b32 s101, v239, 56
	v_lshrrev_b32_e32 v180, 2, v1
	v_and_b32_e32 v180, 12, v180
	v_ashrrev_i32_e32 v181, 6, v1
	v_lshl_or_b32 v180, v181, 5, v180
	v_mov_b32_e32 v181, 0
	s_nop 1
	v_lshl_add_u64 v[180:181], v[180:181], 2, s[100:101]
	global_load_dwordx4 v[182:185], v[180:181], off offset:1024
	global_load_dwordx4 v[186:189], v[180:181], off offset:1088
	s_branch .LBB0_1965
.LBB0_1964:
	s_or_b64 exec, exec, s[4:5]
	v_and_b32_e32 v74, 0x3fc, v100
	s_waitcnt vmcnt(0)
	v_lshl_add_u64 v[66:67], s[0:1], 0, v[74:75]
	v_add_co_u32_e32 v68, vcc, 0x1000, v66
	s_waitcnt lgkmcnt(0)
	s_nop 0
	v_addc_co_u32_e32 v69, vcc, 0, v67, vcc
	v_add_co_u32_e32 v70, vcc, 0x2000, v66
	s_barrier
	s_nop 0
	v_addc_co_u32_e32 v71, vcc, 0, v67, vcc
	global_load_dword v123, v[68:69], off
	global_load_dword v122, v[68:69], off offset:1024
	global_load_dword v120, v[68:69], off offset:2048
	global_load_dword v118, v[68:69], off offset:3072
	global_load_dword v121, v[70:71], off
	global_load_dword v119, v[70:71], off offset:1024
	global_load_dword v117, v[70:71], off offset:2048
	global_load_dword v116, v[70:71], off offset:3072
	global_load_dword v128, v74, s[0:1]
	global_load_dword v127, v74, s[0:1] offset:1024
	global_load_dword v126, v74, s[0:1] offset:2048
	global_load_dword v125, v74, s[0:1] offset:3072
	v_add_co_u32_e32 v68, vcc, 0x3000, v66
	v_readlane_b32 s4, v239, 1
	s_nop 0
	v_addc_co_u32_e32 v69, vcc, 0, v67, vcc
	v_add_co_u32_e32 v70, vcc, s30, v66
	v_readlane_b32 s18, v239, 15
	v_readlane_b32 s19, v239, 16
	v_addc_co_u32_e32 v71, vcc, 0, v67, vcc
	s_nop 3
	global_load_dword v124, v74, s[18:19] offset:1024
	global_load_dword v147, v[68:69], off
	global_load_dword v146, v[68:69], off offset:1024
	global_load_dword v144, v[68:69], off offset:2048
	global_load_dword v142, v[68:69], off offset:3072
	global_load_dword v140, v[70:71], off
	global_load_dword v138, v[70:71], off offset:1024
	global_load_dword v136, v[70:71], off offset:2048
	global_load_dword v133, v[70:71], off offset:3072
	v_add_co_u32_e32 v68, vcc, 0x5000, v66
	v_readlane_b32 s5, v239, 2
	s_nop 0
	v_addc_co_u32_e32 v69, vcc, 0, v67, vcc
	v_add_co_u32_e32 v70, vcc, 0x6000, v66
	v_readlane_b32 s6, v239, 3
	s_nop 0
	v_addc_co_u32_e32 v71, vcc, 0, v67, vcc
	global_load_dword v145, v[68:69], off
	global_load_dword v143, v[68:69], off offset:1024
	global_load_dword v141, v[68:69], off offset:2048
	global_load_dword v139, v[68:69], off offset:3072
	global_load_dword v137, v[70:71], off
	global_load_dword v134, v[70:71], off offset:1024
	global_load_dword v131, v[70:71], off offset:2048
	global_load_dword v129, v[70:71], off offset:3072
	v_add_co_u32_e32 v66, vcc, 0x7000, v66
	v_readlane_b32 s7, v239, 4
	s_nop 0
	v_addc_co_u32_e32 v67, vcc, 0, v67, vcc
	global_load_dword v135, v[66:67], off
	global_load_dword v132, v[66:67], off offset:1024
	global_load_dword v130, v[66:67], off offset:2048
	v_lshlrev_b32_e32 v66, 6, v114
	v_and_b32_e32 v152, 0xffffc000, v66
	v_add3_u32 v66, 0, v152, v74
	ds_read2st64_b32 v[148:149], v66 offset1:4
	ds_read2st64_b32 v[150:151], v66 offset0:8 offset1:12
	ds_read2st64_b32 v[108:109], v66 offset0:16 offset1:20
	ds_read2st64_b32 v[106:107], v66 offset0:24 offset1:28
	ds_read2st64_b32 v[104:105], v66 offset0:32 offset1:36
	ds_read2st64_b32 v[102:103], v66 offset0:40 offset1:44
	ds_read2st64_b32 v[100:101], v66 offset0:48 offset1:52
	ds_read2st64_b32 v[98:99], v66 offset0:56 offset1:60
	ds_read2st64_b32 v[96:97], v66 offset0:64 offset1:68
	ds_read2st64_b32 v[94:95], v66 offset0:72 offset1:76
	ds_read2st64_b32 v[92:93], v66 offset0:80 offset1:84
	ds_read2st64_b32 v[90:91], v66 offset0:88 offset1:92
	ds_read2st64_b32 v[88:89], v66 offset0:96 offset1:100
	ds_read2st64_b32 v[86:87], v66 offset0:104 offset1:108
	ds_read2st64_b32 v[84:85], v66 offset0:112 offset1:116
	ds_read2st64_b32 v[82:83], v66 offset0:120 offset1:124
	ds_read2st64_b32 v[80:81], v66 offset0:128 offset1:132
	ds_read2st64_b32 v[78:79], v66 offset0:136 offset1:140
	ds_read2st64_b32 v[76:77], v66 offset0:144 offset1:148
	ds_read2st64_b32 v[72:73], v66 offset0:152 offset1:156
	ds_read2st64_b32 v[70:71], v66 offset0:160 offset1:164
	ds_read2st64_b32 v[68:69], v66 offset0:168 offset1:172
	ds_read2st64_b32 v[66:67], v66 offset0:176 offset1:180
	v_add3_u32 v74, s40, v152, v74
	v_readlane_b32 s8, v239, 5
	v_readlane_b32 s9, v239, 6
	v_readlane_b32 s10, v239, 7
	v_readlane_b32 s11, v239, 8
	v_readlane_b32 s12, v239, 9
	v_readlane_b32 s13, v239, 10
	v_readlane_b32 s14, v239, 11
	v_readlane_b32 s15, v239, 12
	v_readlane_b32 s16, v239, 13
	v_readlane_b32 s17, v239, 14
	v_readlane_b32 s4, v239, 49
	v_readlane_b32 s5, v239, 50
	v_readlane_b32 s6, v239, 51
	v_readlane_b32 s7, v239, 52
	v_readlane_b32 s10, v239, 55
	v_readlane_b32 s11, v239, 56
	s_add_i32 s46, s46, s68
	v_readlane_b32 s8, v239, 53
	v_readlane_b32 s9, v239, 54
	v_readlane_b32 s12, v239, 57
	v_readlane_b32 s13, v239, 58
	v_readlane_b32 s14, v239, 59
	v_readlane_b32 s15, v239, 60
	v_readlane_b32 s16, v239, 61
	v_readlane_b32 s17, v239, 62
	v_readlane_b32 s18, v239, 63
	v_readlane_b32 s19, v238, 0
	s_waitcnt vmcnt(19) lgkmcnt(14)
	v_fma_f32 v148, v128, v148, v124
	v_fmac_f32_e32 v148, v127, v149
	v_fma_f32 v149, v128, v149, v124
	v_fmac_f32_e32 v149, v127, v150
	v_fmac_f32_e32 v148, v126, v150
	v_fmac_f32_e32 v149, v126, v151
	v_fmac_f32_e32 v148, v125, v151
	v_fmac_f32_e32 v149, v125, v108
	v_fmac_f32_e32 v148, v123, v108
	v_fmac_f32_e32 v149, v123, v109
	v_fmac_f32_e32 v148, v122, v109
	v_fmac_f32_e32 v149, v122, v106
	v_fmac_f32_e32 v148, v120, v106
	v_fmac_f32_e32 v149, v120, v107
	v_fmac_f32_e32 v148, v118, v107
	v_fmac_f32_e32 v149, v118, v104
	v_fmac_f32_e32 v148, v121, v104
	v_fmac_f32_e32 v149, v121, v105
	v_fmac_f32_e32 v148, v119, v105
	v_fmac_f32_e32 v149, v119, v102
	v_fmac_f32_e32 v148, v117, v102
	v_fmac_f32_e32 v149, v117, v103
	v_fmac_f32_e32 v148, v116, v103
	v_fmac_f32_e32 v149, v116, v100
	s_waitcnt vmcnt(18)
	v_fmac_f32_e32 v148, v147, v100
	v_fmac_f32_e32 v149, v147, v101
	s_waitcnt vmcnt(17)
	v_fmac_f32_e32 v148, v146, v101
	v_fmac_f32_e32 v149, v146, v98
	s_waitcnt vmcnt(16)
	v_fmac_f32_e32 v148, v144, v98
	v_fmac_f32_e32 v149, v144, v99
	s_waitcnt vmcnt(15)
	v_fmac_f32_e32 v148, v142, v99
	v_fmac_f32_e32 v149, v142, v96
	s_waitcnt vmcnt(14)
	v_fmac_f32_e32 v148, v140, v96
	v_fmac_f32_e32 v149, v140, v97
	s_waitcnt vmcnt(13)
	v_fmac_f32_e32 v148, v138, v97
	s_waitcnt lgkmcnt(13)
	v_fmac_f32_e32 v149, v138, v94
	s_waitcnt vmcnt(12)
	v_fmac_f32_e32 v148, v136, v94
	v_fmac_f32_e32 v149, v136, v95
	s_waitcnt vmcnt(11)
	v_fmac_f32_e32 v148, v133, v95
	s_waitcnt lgkmcnt(12)
	v_fmac_f32_e32 v149, v133, v92
	s_waitcnt vmcnt(10)
	v_fmac_f32_e32 v148, v145, v92
	v_fmac_f32_e32 v149, v145, v93
	s_waitcnt vmcnt(9)
	v_fmac_f32_e32 v148, v143, v93
	s_waitcnt lgkmcnt(11)
	v_fmac_f32_e32 v149, v143, v90
	s_waitcnt vmcnt(8)
	v_fmac_f32_e32 v148, v141, v90
	v_fmac_f32_e32 v149, v141, v91
	s_waitcnt vmcnt(7)
	v_fmac_f32_e32 v148, v139, v91
	s_waitcnt lgkmcnt(10)
	v_fmac_f32_e32 v149, v139, v88
	s_waitcnt vmcnt(6)
	v_fmac_f32_e32 v148, v137, v88
	v_fmac_f32_e32 v149, v137, v89
	s_waitcnt vmcnt(5)
	v_fmac_f32_e32 v148, v134, v89
	s_waitcnt lgkmcnt(9)
	v_fmac_f32_e32 v149, v134, v86
	s_waitcnt vmcnt(4)
	v_fmac_f32_e32 v148, v131, v86
	v_fmac_f32_e32 v149, v131, v87
	s_waitcnt vmcnt(3)
	v_fmac_f32_e32 v148, v129, v87
	s_waitcnt lgkmcnt(8)
	v_fmac_f32_e32 v149, v129, v84
	s_waitcnt vmcnt(2)
	v_fmac_f32_e32 v148, v135, v84
	v_fmac_f32_e32 v149, v135, v85
	s_waitcnt vmcnt(1)
	v_fmac_f32_e32 v148, v132, v85
	s_waitcnt lgkmcnt(7)
	v_fmac_f32_e32 v149, v132, v82
	s_waitcnt vmcnt(0)
	v_fmac_f32_e32 v148, v130, v82
	v_fmac_f32_e32 v149, v130, v83
	ds_write2st64_b32 v74, v148, v149 offset1:4
	v_fma_f32 v148, v128, v150, v124
	v_fmac_f32_e32 v148, v127, v151
	v_fma_f32 v149, v128, v151, v124
	v_fmac_f32_e32 v148, v126, v108
	v_fmac_f32_e32 v149, v127, v108
	v_fma_f32 v108, v128, v108, v124
	v_fmac_f32_e32 v148, v125, v109
	v_fmac_f32_e32 v149, v126, v109
	v_fmac_f32_e32 v108, v127, v109
	v_fma_f32 v109, v128, v109, v124
	v_fmac_f32_e32 v148, v123, v106
	v_fmac_f32_e32 v149, v125, v106
	v_fmac_f32_e32 v108, v126, v106
	v_fmac_f32_e32 v109, v127, v106
	v_fma_f32 v106, v128, v106, v124
	v_fmac_f32_e32 v148, v122, v107
	v_fmac_f32_e32 v149, v123, v107
	v_fmac_f32_e32 v108, v125, v107
	v_fmac_f32_e32 v109, v126, v107
	v_fmac_f32_e32 v106, v127, v107
	v_fma_f32 v107, v128, v107, v124
	v_fmac_f32_e32 v148, v120, v104
	v_fmac_f32_e32 v149, v122, v104
	v_fmac_f32_e32 v108, v123, v104
	v_fmac_f32_e32 v109, v125, v104
	v_fmac_f32_e32 v106, v126, v104
	v_fmac_f32_e32 v107, v127, v104
	v_fma_f32 v104, v128, v104, v124
	v_fmac_f32_e32 v148, v118, v105
	v_fmac_f32_e32 v149, v120, v105
	v_fmac_f32_e32 v108, v122, v105
	v_fmac_f32_e32 v109, v123, v105
	v_fmac_f32_e32 v106, v125, v105
	v_fmac_f32_e32 v107, v126, v105
	v_fmac_f32_e32 v104, v127, v105
	v_fma_f32 v105, v128, v105, v124
	v_fmac_f32_e32 v148, v121, v102
	v_fmac_f32_e32 v149, v118, v102
	v_fmac_f32_e32 v108, v120, v102
	v_fmac_f32_e32 v109, v122, v102
	v_fmac_f32_e32 v106, v123, v102
	v_fmac_f32_e32 v107, v125, v102
	v_fmac_f32_e32 v104, v126, v102
	v_fmac_f32_e32 v105, v127, v102
	v_fma_f32 v102, v128, v102, v124
	v_fmac_f32_e32 v148, v119, v103
	v_fmac_f32_e32 v149, v121, v103
	v_fmac_f32_e32 v108, v118, v103
	v_fmac_f32_e32 v109, v120, v103
	v_fmac_f32_e32 v106, v122, v103
	v_fmac_f32_e32 v107, v123, v103
	v_fmac_f32_e32 v104, v125, v103
	v_fmac_f32_e32 v105, v126, v103
	v_fmac_f32_e32 v102, v127, v103
	v_fma_f32 v103, v128, v103, v124
	v_fmac_f32_e32 v148, v117, v100
	v_fmac_f32_e32 v149, v119, v100
	v_fmac_f32_e32 v108, v121, v100
	v_fmac_f32_e32 v109, v118, v100
	v_fmac_f32_e32 v106, v120, v100
	v_fmac_f32_e32 v107, v122, v100
	v_fmac_f32_e32 v104, v123, v100
	v_fmac_f32_e32 v105, v125, v100
	v_fmac_f32_e32 v102, v126, v100
	v_fmac_f32_e32 v103, v127, v100
	v_fma_f32 v100, v128, v100, v124
	v_fmac_f32_e32 v148, v116, v101
	v_fmac_f32_e32 v149, v117, v101
	v_fmac_f32_e32 v108, v119, v101
	v_fmac_f32_e32 v109, v121, v101
	v_fmac_f32_e32 v106, v118, v101
	v_fmac_f32_e32 v107, v120, v101
	v_fmac_f32_e32 v104, v122, v101
	v_fmac_f32_e32 v105, v123, v101
	v_fmac_f32_e32 v102, v125, v101
	v_fmac_f32_e32 v103, v126, v101
	v_fmac_f32_e32 v100, v127, v101
	v_fma_f32 v101, v128, v101, v124
	v_fmac_f32_e32 v148, v147, v98
	v_fmac_f32_e32 v149, v116, v98
	v_fmac_f32_e32 v108, v117, v98
	v_fmac_f32_e32 v109, v119, v98
	v_fmac_f32_e32 v106, v121, v98
	v_fmac_f32_e32 v107, v118, v98
	v_fmac_f32_e32 v104, v120, v98
	v_fmac_f32_e32 v105, v122, v98
	v_fmac_f32_e32 v102, v123, v98
	v_fmac_f32_e32 v103, v125, v98
	v_fmac_f32_e32 v100, v126, v98
	v_fmac_f32_e32 v101, v127, v98
	v_fma_f32 v98, v128, v98, v124
	v_fmac_f32_e32 v124, v128, v99
	v_fmac_f32_e32 v98, v127, v99
	v_fmac_f32_e32 v124, v127, v96
	v_fmac_f32_e32 v101, v126, v99
	v_fmac_f32_e32 v98, v126, v96
	v_fmac_f32_e32 v124, v126, v97
	v_fmac_f32_e32 v100, v125, v99
	v_fmac_f32_e32 v101, v125, v96
	v_fmac_f32_e32 v98, v125, v97
	v_fmac_f32_e32 v124, v125, v94
	v_fmac_f32_e32 v103, v123, v99
	v_fmac_f32_e32 v100, v123, v96
	v_fmac_f32_e32 v101, v123, v97
	v_fmac_f32_e32 v98, v123, v94
	v_fmac_f32_e32 v124, v123, v95
	v_fmac_f32_e32 v102, v122, v99
	v_fmac_f32_e32 v103, v122, v96
	v_fmac_f32_e32 v100, v122, v97
	v_fmac_f32_e32 v101, v122, v94
	v_fmac_f32_e32 v98, v122, v95
	v_fmac_f32_e32 v124, v122, v92
	v_fmac_f32_e32 v105, v120, v99
	v_fmac_f32_e32 v102, v120, v96
	v_fmac_f32_e32 v103, v120, v97
	v_fmac_f32_e32 v100, v120, v94
	v_fmac_f32_e32 v101, v120, v95
	v_fmac_f32_e32 v98, v120, v92
	v_fmac_f32_e32 v124, v120, v93
	v_fmac_f32_e32 v104, v118, v99
	v_fmac_f32_e32 v105, v118, v96
	v_fmac_f32_e32 v102, v118, v97
	v_fmac_f32_e32 v103, v118, v94
	v_fmac_f32_e32 v100, v118, v95
	v_fmac_f32_e32 v101, v118, v92
	v_fmac_f32_e32 v98, v118, v93
	v_fmac_f32_e32 v124, v118, v90
	v_fmac_f32_e32 v107, v121, v99
	v_fmac_f32_e32 v104, v121, v96
	v_fmac_f32_e32 v105, v121, v97
	v_fmac_f32_e32 v102, v121, v94
	v_fmac_f32_e32 v103, v121, v95
	v_fmac_f32_e32 v100, v121, v92
	v_fmac_f32_e32 v101, v121, v93
	v_fmac_f32_e32 v98, v121, v90
	v_fmac_f32_e32 v124, v121, v91
	v_fmac_f32_e32 v106, v119, v99
	v_fmac_f32_e32 v107, v119, v96
	v_fmac_f32_e32 v104, v119, v97
	v_fmac_f32_e32 v105, v119, v94
	v_fmac_f32_e32 v102, v119, v95
	v_fmac_f32_e32 v103, v119, v92
	v_fmac_f32_e32 v100, v119, v93
	v_fmac_f32_e32 v101, v119, v90
	v_fmac_f32_e32 v98, v119, v91
	v_fmac_f32_e32 v124, v119, v88
	v_fmac_f32_e32 v109, v117, v99
	v_fmac_f32_e32 v106, v117, v96
	v_fmac_f32_e32 v107, v117, v97
	v_fmac_f32_e32 v104, v117, v94
	v_fmac_f32_e32 v105, v117, v95
	v_fmac_f32_e32 v102, v117, v92
	v_fmac_f32_e32 v103, v117, v93
	v_fmac_f32_e32 v100, v117, v90
	v_fmac_f32_e32 v101, v117, v91
	v_fmac_f32_e32 v98, v117, v88
	v_fmac_f32_e32 v124, v117, v89
	v_fmac_f32_e32 v108, v116, v99
	v_fmac_f32_e32 v109, v116, v96
	v_fmac_f32_e32 v106, v116, v97
	v_fmac_f32_e32 v107, v116, v94
	v_fmac_f32_e32 v104, v116, v95
	v_fmac_f32_e32 v105, v116, v92
	v_fmac_f32_e32 v102, v116, v93
	v_fmac_f32_e32 v103, v116, v90
	v_fmac_f32_e32 v100, v116, v91
	v_fmac_f32_e32 v101, v116, v88
	v_fmac_f32_e32 v98, v116, v89
	v_fmac_f32_e32 v124, v116, v86
	v_fmac_f32_e32 v149, v147, v99
	v_fmac_f32_e32 v108, v147, v96
	v_fmac_f32_e32 v109, v147, v97
	v_fmac_f32_e32 v106, v147, v94
	v_fmac_f32_e32 v107, v147, v95
	v_fmac_f32_e32 v104, v147, v92
	v_fmac_f32_e32 v105, v147, v93
	v_fmac_f32_e32 v102, v147, v90
	v_fmac_f32_e32 v103, v147, v91
	v_fmac_f32_e32 v100, v147, v88
	v_fmac_f32_e32 v101, v147, v89
	v_fmac_f32_e32 v98, v147, v86
	v_fmac_f32_e32 v124, v147, v87
	v_fmac_f32_e32 v148, v146, v99
	v_fmac_f32_e32 v149, v146, v96
	v_fmac_f32_e32 v108, v146, v97
	v_fmac_f32_e32 v109, v146, v94
	v_fmac_f32_e32 v106, v146, v95
	v_fmac_f32_e32 v107, v146, v92
	v_fmac_f32_e32 v104, v146, v93
	v_fmac_f32_e32 v105, v146, v90
	v_fmac_f32_e32 v102, v146, v91
	v_fmac_f32_e32 v103, v146, v88
	v_fmac_f32_e32 v100, v146, v89
	v_fmac_f32_e32 v101, v146, v86
	v_fmac_f32_e32 v98, v146, v87
	v_fmac_f32_e32 v124, v146, v84
	v_fmac_f32_e32 v148, v144, v96
	v_fmac_f32_e32 v149, v144, v97
	v_fmac_f32_e32 v108, v144, v94
	v_fmac_f32_e32 v109, v144, v95
	v_fmac_f32_e32 v106, v144, v92
	v_fmac_f32_e32 v107, v144, v93
	v_fmac_f32_e32 v104, v144, v90
	v_fmac_f32_e32 v105, v144, v91
	v_fmac_f32_e32 v102, v144, v88
	v_fmac_f32_e32 v103, v144, v89
	v_fmac_f32_e32 v100, v144, v86
	v_fmac_f32_e32 v101, v144, v87
	v_fmac_f32_e32 v98, v144, v84
	v_fmac_f32_e32 v124, v144, v85
	v_fmac_f32_e32 v148, v142, v97
	v_fmac_f32_e32 v149, v142, v94
	v_fmac_f32_e32 v108, v142, v95
	v_fmac_f32_e32 v109, v142, v92
	v_fmac_f32_e32 v106, v142, v93
	v_fmac_f32_e32 v107, v142, v90
	v_fmac_f32_e32 v104, v142, v91
	v_fmac_f32_e32 v105, v142, v88
	v_fmac_f32_e32 v102, v142, v89
	v_fmac_f32_e32 v103, v142, v86
	v_fmac_f32_e32 v100, v142, v87
	v_fmac_f32_e32 v101, v142, v84
	v_fmac_f32_e32 v98, v142, v85
	v_fmac_f32_e32 v124, v142, v82
	v_fmac_f32_e32 v148, v140, v94
	v_fmac_f32_e32 v149, v140, v95
	v_fmac_f32_e32 v108, v140, v92
	v_fmac_f32_e32 v109, v140, v93
	v_fmac_f32_e32 v106, v140, v90
	v_fmac_f32_e32 v107, v140, v91
	v_fmac_f32_e32 v104, v140, v88
	v_fmac_f32_e32 v105, v140, v89
	v_fmac_f32_e32 v102, v140, v86
	v_fmac_f32_e32 v103, v140, v87
	v_fmac_f32_e32 v100, v140, v84
	v_fmac_f32_e32 v101, v140, v85
	v_fmac_f32_e32 v98, v140, v82
	v_fmac_f32_e32 v124, v140, v83
	v_fmac_f32_e32 v148, v138, v95
	v_fmac_f32_e32 v149, v138, v92
	v_fmac_f32_e32 v108, v138, v93
	v_fmac_f32_e32 v109, v138, v90
	v_fmac_f32_e32 v106, v138, v91
	v_fmac_f32_e32 v107, v138, v88
	v_fmac_f32_e32 v104, v138, v89
	v_fmac_f32_e32 v105, v138, v86
	v_fmac_f32_e32 v102, v138, v87
	v_fmac_f32_e32 v103, v138, v84
	v_fmac_f32_e32 v100, v138, v85
	v_fmac_f32_e32 v101, v138, v82
	v_fmac_f32_e32 v98, v138, v83
	s_waitcnt lgkmcnt(7)
	v_fmac_f32_e32 v124, v138, v80
	v_fmac_f32_e32 v148, v136, v92
	v_fmac_f32_e32 v149, v136, v93
	v_fmac_f32_e32 v108, v136, v90
	v_fmac_f32_e32 v109, v136, v91
	v_fmac_f32_e32 v106, v136, v88
	v_fmac_f32_e32 v107, v136, v89
	v_fmac_f32_e32 v104, v136, v86
	v_fmac_f32_e32 v105, v136, v87
	v_fmac_f32_e32 v102, v136, v84
	v_fmac_f32_e32 v103, v136, v85
	v_fmac_f32_e32 v100, v136, v82
	v_fmac_f32_e32 v101, v136, v83
	v_fmac_f32_e32 v98, v136, v80
	v_fmac_f32_e32 v124, v136, v81
	v_fmac_f32_e32 v148, v133, v93
	v_fmac_f32_e32 v149, v133, v90
	v_fmac_f32_e32 v108, v133, v91
	v_fmac_f32_e32 v109, v133, v88
	v_fmac_f32_e32 v106, v133, v89
	v_fmac_f32_e32 v107, v133, v86
	v_fmac_f32_e32 v104, v133, v87
	v_fmac_f32_e32 v105, v133, v84
	v_fmac_f32_e32 v102, v133, v85
	v_fmac_f32_e32 v103, v133, v82
	v_fmac_f32_e32 v100, v133, v83
	v_fmac_f32_e32 v101, v133, v80
	v_fmac_f32_e32 v98, v133, v81
	s_waitcnt lgkmcnt(6)
	v_fmac_f32_e32 v124, v133, v78
	v_fmac_f32_e32 v148, v145, v90
	v_fmac_f32_e32 v149, v145, v91
	v_fmac_f32_e32 v108, v145, v88
	v_fmac_f32_e32 v109, v145, v89
	v_fmac_f32_e32 v106, v145, v86
	v_fmac_f32_e32 v107, v145, v87
	v_fmac_f32_e32 v104, v145, v84
	v_fmac_f32_e32 v105, v145, v85
	v_fmac_f32_e32 v102, v145, v82
	v_fmac_f32_e32 v103, v145, v83
	v_fmac_f32_e32 v100, v145, v80
	v_fmac_f32_e32 v101, v145, v81
	v_fmac_f32_e32 v98, v145, v78
	v_fmac_f32_e32 v124, v145, v79
	v_fmac_f32_e32 v148, v143, v91
	v_fmac_f32_e32 v149, v143, v88
	v_fmac_f32_e32 v108, v143, v89
	v_fmac_f32_e32 v109, v143, v86
	v_fmac_f32_e32 v106, v143, v87
	v_fmac_f32_e32 v107, v143, v84
	v_fmac_f32_e32 v104, v143, v85
	v_fmac_f32_e32 v105, v143, v82
	v_fmac_f32_e32 v102, v143, v83
	v_fmac_f32_e32 v103, v143, v80
	v_fmac_f32_e32 v100, v143, v81
	v_fmac_f32_e32 v101, v143, v78
	v_fmac_f32_e32 v98, v143, v79
	s_waitcnt lgkmcnt(5)
	v_fmac_f32_e32 v124, v143, v76
	v_fmac_f32_e32 v148, v141, v88
	v_fmac_f32_e32 v149, v141, v89
	v_fmac_f32_e32 v108, v141, v86
	v_fmac_f32_e32 v109, v141, v87
	v_fmac_f32_e32 v106, v141, v84
	v_fmac_f32_e32 v107, v141, v85
	v_fmac_f32_e32 v104, v141, v82
	v_fmac_f32_e32 v105, v141, v83
	v_fmac_f32_e32 v102, v141, v80
	v_fmac_f32_e32 v103, v141, v81
	v_fmac_f32_e32 v100, v141, v78
	v_fmac_f32_e32 v101, v141, v79
	v_fmac_f32_e32 v98, v141, v76
	v_fmac_f32_e32 v124, v141, v77
	v_fmac_f32_e32 v148, v139, v89
	v_fmac_f32_e32 v149, v139, v86
	v_fmac_f32_e32 v108, v139, v87
	v_fmac_f32_e32 v109, v139, v84
	v_fmac_f32_e32 v106, v139, v85
	v_fmac_f32_e32 v107, v139, v82
	v_fmac_f32_e32 v104, v139, v83
	v_fmac_f32_e32 v105, v139, v80
	v_fmac_f32_e32 v102, v139, v81
	v_fmac_f32_e32 v103, v139, v78
	v_fmac_f32_e32 v100, v139, v79
	v_fmac_f32_e32 v101, v139, v76
	v_fmac_f32_e32 v98, v139, v77
	s_waitcnt lgkmcnt(4)
	v_fmac_f32_e32 v124, v139, v72
	v_fmac_f32_e32 v148, v137, v86
	v_fmac_f32_e32 v149, v137, v87
	v_fmac_f32_e32 v108, v137, v84
	v_fmac_f32_e32 v109, v137, v85
	v_fmac_f32_e32 v106, v137, v82
	v_fmac_f32_e32 v107, v137, v83
	v_fmac_f32_e32 v104, v137, v80
	v_fmac_f32_e32 v105, v137, v81
	v_fmac_f32_e32 v102, v137, v78
	v_fmac_f32_e32 v103, v137, v79
	v_fmac_f32_e32 v100, v137, v76
	v_fmac_f32_e32 v101, v137, v77
	v_fmac_f32_e32 v98, v137, v72
	v_fmac_f32_e32 v124, v137, v73
	v_fmac_f32_e32 v148, v134, v87
	v_fmac_f32_e32 v149, v134, v84
	v_fmac_f32_e32 v108, v134, v85
	v_fmac_f32_e32 v109, v134, v82
	v_fmac_f32_e32 v106, v134, v83
	v_fmac_f32_e32 v107, v134, v80
	v_fmac_f32_e32 v104, v134, v81
	v_fmac_f32_e32 v105, v134, v78
	v_fmac_f32_e32 v102, v134, v79
	v_fmac_f32_e32 v103, v134, v76
	v_fmac_f32_e32 v100, v134, v77
	v_fmac_f32_e32 v101, v134, v72
	v_fmac_f32_e32 v98, v134, v73
	s_waitcnt lgkmcnt(3)
	v_fmac_f32_e32 v124, v134, v70
	v_fmac_f32_e32 v148, v131, v84
	v_fmac_f32_e32 v149, v131, v85
	v_fmac_f32_e32 v108, v131, v82
	v_fmac_f32_e32 v109, v131, v83
	v_fmac_f32_e32 v106, v131, v80
	v_fmac_f32_e32 v107, v131, v81
	v_fmac_f32_e32 v104, v131, v78
	v_fmac_f32_e32 v105, v131, v79
	v_fmac_f32_e32 v102, v131, v76
	v_fmac_f32_e32 v103, v131, v77
	v_fmac_f32_e32 v100, v131, v72
	v_fmac_f32_e32 v101, v131, v73
	v_fmac_f32_e32 v98, v131, v70
	v_fmac_f32_e32 v124, v131, v71
	v_fmac_f32_e32 v148, v129, v85
	v_fmac_f32_e32 v149, v129, v82
	v_fmac_f32_e32 v108, v129, v83
	v_fmac_f32_e32 v109, v129, v80
	v_fmac_f32_e32 v106, v129, v81
	v_fmac_f32_e32 v107, v129, v78
	v_fmac_f32_e32 v104, v129, v79
	v_fmac_f32_e32 v105, v129, v76
	v_fmac_f32_e32 v102, v129, v77
	v_fmac_f32_e32 v103, v129, v72
	v_fmac_f32_e32 v100, v129, v73
	v_fmac_f32_e32 v101, v129, v70
	v_fmac_f32_e32 v98, v129, v71
	s_waitcnt lgkmcnt(2)
	v_fmac_f32_e32 v124, v129, v68
	v_fmac_f32_e32 v148, v135, v82
	v_fmac_f32_e32 v149, v135, v83
	v_fmac_f32_e32 v108, v135, v80
	v_fmac_f32_e32 v109, v135, v81
	v_fmac_f32_e32 v106, v135, v78
	v_fmac_f32_e32 v107, v135, v79
	v_fmac_f32_e32 v104, v135, v76
	v_fmac_f32_e32 v105, v135, v77
	v_fmac_f32_e32 v102, v135, v72
	v_fmac_f32_e32 v103, v135, v73
	v_fmac_f32_e32 v100, v135, v70
	v_fmac_f32_e32 v101, v135, v71
	v_fmac_f32_e32 v98, v135, v68
	v_fmac_f32_e32 v124, v135, v69
	v_fmac_f32_e32 v148, v132, v83
	v_fmac_f32_e32 v149, v132, v80
	v_fmac_f32_e32 v108, v132, v81
	v_fmac_f32_e32 v109, v132, v78
	v_fmac_f32_e32 v106, v132, v79
	v_fmac_f32_e32 v107, v132, v76
	v_fmac_f32_e32 v104, v132, v77
	v_fmac_f32_e32 v105, v132, v72
	v_fmac_f32_e32 v102, v132, v73
	v_fmac_f32_e32 v103, v132, v70
	v_fmac_f32_e32 v100, v132, v71
	v_fmac_f32_e32 v101, v132, v68
	v_fmac_f32_e32 v98, v132, v69
	s_waitcnt lgkmcnt(1)
	v_fmac_f32_e32 v124, v132, v66
	v_fmac_f32_e32 v148, v130, v80
	v_fmac_f32_e32 v149, v130, v81
	v_fmac_f32_e32 v108, v130, v78
	v_fmac_f32_e32 v109, v130, v79
	v_fmac_f32_e32 v106, v130, v76
	v_fmac_f32_e32 v107, v130, v77
	v_fmac_f32_e32 v104, v130, v72
	v_fmac_f32_e32 v105, v130, v73
	v_fmac_f32_e32 v102, v130, v70
	v_fmac_f32_e32 v103, v130, v71
	v_fmac_f32_e32 v100, v130, v68
	v_fmac_f32_e32 v101, v130, v69
	v_fmac_f32_e32 v98, v130, v66
	v_fmac_f32_e32 v124, v130, v67
	ds_write2st64_b32 v74, v148, v149 offset0:8 offset1:12
	ds_write2st64_b32 v74, v108, v109 offset0:16 offset1:20
	ds_write2st64_b32 v74, v106, v107 offset0:24 offset1:28
	ds_write2st64_b32 v74, v104, v105 offset0:32 offset1:36
	ds_write2st64_b32 v74, v102, v103 offset0:40 offset1:44
	ds_write2st64_b32 v74, v100, v101 offset0:48 offset1:52
	ds_write2st64_b32 v74, v98, v124 offset0:56 offset1:60
	v_lshlrev_b32_e32 v74, 2, v115
	v_add_u32_e32 v86, s40, v74
	v_lshl_add_u32 v88, v113, 12, v86
	s_waitcnt lgkmcnt(0)
	s_barrier
	global_load_dwordx4 v[66:69], v74, s[4:5] offset:1024
	global_load_dwordx4 v[70:73], v74, s[6:7] offset:1024
	ds_read_b128 v[78:81], v88
	v_and_b32_e32 v74, 64, v110
	v_add_u32_e32 v74, 64, v74
	v_xor_b32_e32 v76, 1, v110
	v_cmp_lt_i32_e32 vcc, v76, v74
	s_waitcnt lgkmcnt(0)
	v_mov_b32_e32 v77, v80
	v_mov_b32_e32 v82, v78
	v_cndmask_b32_e32 v76, v110, v76, vcc
	v_lshlrev_b32_e32 v89, 2, v76
	v_mov_b32_e32 v76, v79
	v_mov_b32_e32 v83, v81
	v_pk_add_f32 v[76:77], v[76:77], v[82:83]
	v_xor_b32_e32 v82, 2, v110
	v_add_f32_e32 v76, v76, v77
	v_cmp_lt_i32_e32 vcc, v82, v74
	v_lshl_or_b32 v87, v113, 2, 1
	s_waitcnt lgkmcnt(0)
	s_nop 1
	v_add_f32_dpp v76, v76, v76 quad_perm:[1,0,3,2] row_mask:0xf bank_mask:0xf
	v_cndmask_b32_e32 v82, v110, v82, vcc
	v_lshlrev_b32_e32 v90, 2, v82
	v_xor_b32_e32 v82, 4, v110
	v_cmp_lt_i32_e32 vcc, v82, v74
	s_waitcnt lgkmcnt(0)
	s_nop 1
	v_add_f32_dpp v76, v76, v76 quad_perm:[2,3,0,1] row_mask:0xf bank_mask:0xf
	v_cndmask_b32_e32 v82, v110, v82, vcc
	v_lshlrev_b32_e32 v91, 2, v82
	v_xor_b32_e32 v82, 8, v110
	v_cmp_lt_i32_e32 vcc, v82, v74
	s_waitcnt lgkmcnt(0)
	s_nop 1
	v_add_f32_dpp v76, v76, v76 row_half_mirror row_mask:0xf bank_mask:0xf
	v_cndmask_b32_e32 v82, v110, v82, vcc
	v_lshlrev_b32_e32 v92, 2, v82
	v_xor_b32_e32 v82, 16, v110
	v_cmp_lt_i32_e32 vcc, v82, v74
	s_waitcnt lgkmcnt(0)
	s_nop 1
	v_add_f32_dpp v76, v76, v76 row_mirror row_mask:0xf bank_mask:0xf
	v_cndmask_b32_e32 v82, v110, v82, vcc
	v_lshlrev_b32_e32 v93, 2, v82
	v_xor_b32_e32 v82, 32, v110
	v_cmp_lt_i32_e32 vcc, v82, v74
	s_nop 1
	v_cndmask_b32_e32 v74, v110, v82, vcc
	v_lshlrev_b32_e32 v94, 2, v74
	s_waitcnt lgkmcnt(0)
	v_mov_b32_e32 v77, v76
	v_mov_b32_e32 v254, v76
	s_nop 1
	v_permlane16_swap_b32 v77, v254
	v_add_f32_e32 v74, v77, v254
	s_waitcnt lgkmcnt(0)
	v_mov_b32_e32 v76, v74
	v_mov_b32_e32 v254, v74
	s_nop 1
	v_permlane32_swap_b32 v76, v254
	v_add_f32_e32 v74, v76, v254
	v_fmamk_f32 v83, v74, 0xbb800000, v79
	v_fmamk_f32 v82, v74, 0xbb800000, v78
	v_fmamk_f32 v81, v74, 0xbb800000, v81
	v_fmac_f32_e32 v80, 0xbb800000, v74
	v_pk_mul_f32 v[76:77], v[80:81], v[80:81]
	v_pk_mul_f32 v[78:79], v[82:83], v[82:83]
	s_nop 0
	v_pk_mov_b32 v[84:85], v[78:79], v[76:77] op_sel:[1,0]
	v_mov_b32_e32 v79, v77
	v_pk_add_f32 v[76:77], v[84:85], v[78:79]
	s_waitcnt vmcnt(0)
	v_mov_b32_e32 v78, v70
	v_add_f32_e32 v74, v76, v77
	v_mov_b32_e32 v77, v80
	v_mov_b32_e32 v79, v72
	v_mov_b32_e32 v80, v83
	v_mov_b32_e32 v72, v71
	s_waitcnt lgkmcnt(0)
	s_nop 1
	v_add_f32_dpp v74, v74, v74 quad_perm:[1,0,3,2] row_mask:0xf bank_mask:0xf
	s_waitcnt lgkmcnt(0)
	s_nop 1
	v_add_f32_dpp v74, v74, v74 quad_perm:[2,3,0,1] row_mask:0xf bank_mask:0xf
	s_waitcnt lgkmcnt(0)
	s_nop 1
	v_add_f32_dpp v74, v74, v74 row_half_mirror row_mask:0xf bank_mask:0xf
	s_waitcnt lgkmcnt(0)
	s_nop 1
	v_add_f32_dpp v74, v74, v74 row_mirror row_mask:0xf bank_mask:0xf
	s_waitcnt lgkmcnt(0)
	v_mov_b32_e32 v76, v74
	v_mov_b32_e32 v254, v74
	s_nop 1
	v_permlane16_swap_b32 v76, v254
	v_add_f32_e32 v74, v76, v254
	s_waitcnt lgkmcnt(0)
	v_mov_b32_e32 v76, v74
	v_mov_b32_e32 v254, v74
	s_nop 1
	v_permlane32_swap_b32 v76, v254
	v_add_f32_e32 v74, v76, v254
	v_fmamk_f32 v74, v74, 0x3b800000, v111
	v_mul_f32_e32 v76, 0x4b800000, v74
	v_cmp_gt_f32_e32 vcc, s42, v74
	s_nop 1
	v_cndmask_b32_e32 v74, v74, v76, vcc
	v_rsq_f32_e32 v74, v74
	s_nop 0
	v_mul_f32_e32 v76, 0x45800000, v74
	v_cndmask_b32_e32 v74, v74, v76, vcc
	v_mov_b32_e32 v76, v82
	v_pk_mul_f32 v[84:85], v[76:77], v[74:75] op_sel_hi:[1,0]
	v_mov_b32_e32 v76, v66
	v_mov_b32_e32 v77, v68
	v_pk_fma_f32 v[84:85], v[76:77], v[84:85], v[78:79]
	v_pk_mul_f32 v[80:81], v[80:81], v[74:75] op_sel_hi:[1,0]
	v_mul_f32_e32 v66, 0xbfb8aa3b, v84
	v_mov_b32_e32 v68, v67
	v_exp_f32_e32 v70, v66
	v_pk_fma_f32 v[66:67], v[68:69], v[80:81], v[72:73]
	v_mul_f32_e32 v74, 0xbfb8aa3b, v85
	v_mul_f32_e32 v71, 0xbfb8aa3b, v66
	v_exp_f32_e32 v71, v71
	v_exp_f32_e32 v74, v74
	v_mul_f32_e32 v80, 0xbfb8aa3b, v67
	v_exp_f32_e32 v81, v80
	v_add_f32_e32 v71, 1.0, v71
	v_add_f32_e32 v70, 1.0, v70
	v_rcp_f32_e32 v80, v71
	v_add_f32_e32 v71, 1.0, v74
	v_rcp_f32_e32 v70, v70
	v_rcp_f32_e32 v71, v71
	v_add_f32_e32 v74, 1.0, v81
	v_rcp_f32_e32 v81, v74
	v_lshl_add_u32 v74, v115, 1, s41
	v_pk_mul_f32 v[70:71], v[84:85], v[70:71]
	v_pk_mul_f32 v[66:67], v[66:67], v[80:81]
	v_and_b32_sdwa v80, v71, v112 dst_sel:DWORD dst_unused:UNUSED_PAD src0_sel:WORD_1 src1_sel:DWORD
	v_and_b32_sdwa v81, v70, v112 dst_sel:DWORD dst_unused:UNUSED_PAD src0_sel:WORD_1 src1_sel:DWORD
	v_add3_u32 v70, v70, v81, s43
	v_add3_u32 v71, v71, v80, s43
	v_and_b32_sdwa v80, v67, v112 dst_sel:DWORD dst_unused:UNUSED_PAD src0_sel:WORD_1 src1_sel:DWORD
	v_and_b32_sdwa v81, v66, v112 dst_sel:DWORD dst_unused:UNUSED_PAD src0_sel:WORD_1 src1_sel:DWORD
	v_add3_u32 v67, v67, v80, s43
	v_add3_u32 v66, v66, v81, s43
	v_and_b32_e32 v67, 0xffff0000, v67
	v_and_b32_e32 v66, 0xffff0000, v66
	v_or_b32_sdwa v67, v67, v71 dst_sel:DWORD dst_unused:UNUSED_PAD src0_sel:DWORD src1_sel:WORD_1
	v_or_b32_sdwa v66, v66, v70 dst_sel:DWORD dst_unused:UNUSED_PAD src0_sel:DWORD src1_sel:WORD_1
	v_mad_u64_u32 v[70:71], s[4:5], v113, s44, v[74:75]
	ds_write_b64 v70, v[66:67]
	v_lshl_add_u32 v66, v87, 10, v86
	ds_read_b128 v[80:83], v66
	s_waitcnt lgkmcnt(0)
	v_mov_b32_e32 v66, v81
	v_mov_b32_e32 v67, v82
	v_mov_b32_e32 v70, v80
	v_mov_b32_e32 v71, v83
	v_pk_add_f32 v[66:67], v[66:67], v[70:71]
	s_nop 0
	v_add_f32_e32 v66, v66, v67
	s_waitcnt lgkmcnt(0)
	s_nop 1
	v_add_f32_dpp v66, v66, v66 quad_perm:[1,0,3,2] row_mask:0xf bank_mask:0xf
	s_waitcnt lgkmcnt(0)
	s_nop 1
	v_add_f32_dpp v66, v66, v66 quad_perm:[2,3,0,1] row_mask:0xf bank_mask:0xf
	s_waitcnt lgkmcnt(0)
	s_nop 1
	v_add_f32_dpp v66, v66, v66 row_half_mirror row_mask:0xf bank_mask:0xf
	s_waitcnt lgkmcnt(0)
	s_nop 1
	v_add_f32_dpp v66, v66, v66 row_mirror row_mask:0xf bank_mask:0xf
	s_waitcnt lgkmcnt(0)
	v_mov_b32_e32 v67, v66
	v_mov_b32_e32 v254, v66
	s_nop 1
	v_permlane16_swap_b32 v67, v254
	v_add_f32_e32 v66, v67, v254
	s_waitcnt lgkmcnt(0)
	v_mov_b32_e32 v67, v66
	v_mov_b32_e32 v254, v66
	s_nop 1
	v_permlane32_swap_b32 v67, v254
	v_add_f32_e32 v70, v67, v254
	v_fmamk_f32 v67, v70, 0xbb800000, v81
	v_fmamk_f32 v66, v70, 0xbb800000, v80
	v_fmamk_f32 v83, v70, 0xbb800000, v83
	v_fmac_f32_e32 v82, 0xbb800000, v70
	v_pk_mul_f32 v[70:71], v[82:83], v[82:83]
	v_pk_mul_f32 v[80:81], v[66:67], v[66:67]
	s_nop 0
	v_pk_mov_b32 v[84:85], v[80:81], v[70:71] op_sel:[1,0]
	v_mov_b32_e32 v81, v71
	v_pk_add_f32 v[70:71], v[84:85], v[80:81]
	v_mov_b32_e32 v80, v66
	v_add_f32_e32 v70, v70, v71
	v_mov_b32_e32 v81, v82
	v_mov_b32_e32 v82, v67
	s_waitcnt lgkmcnt(0)
	s_nop 1
	v_add_f32_dpp v70, v70, v70 quad_perm:[1,0,3,2] row_mask:0xf bank_mask:0xf
	s_waitcnt lgkmcnt(0)
	s_nop 1
	v_add_f32_dpp v70, v70, v70 quad_perm:[2,3,0,1] row_mask:0xf bank_mask:0xf
	s_waitcnt lgkmcnt(0)
	s_nop 1
	v_add_f32_dpp v70, v70, v70 row_half_mirror row_mask:0xf bank_mask:0xf
	s_waitcnt lgkmcnt(0)
	s_nop 1
	v_add_f32_dpp v70, v70, v70 row_mirror row_mask:0xf bank_mask:0xf
	s_waitcnt lgkmcnt(0)
	v_mov_b32_e32 v71, v70
	v_mov_b32_e32 v254, v70
	s_nop 1
	v_permlane16_swap_b32 v71, v254
	v_add_f32_e32 v70, v71, v254
	s_waitcnt lgkmcnt(0)
	v_mov_b32_e32 v71, v70
	v_mov_b32_e32 v254, v70
	s_nop 1
	v_permlane32_swap_b32 v71, v254
	v_add_f32_e32 v70, v71, v254
	v_fmamk_f32 v70, v70, 0x3b800000, v111
	v_mul_f32_e32 v71, 0x4b800000, v70
	v_cmp_gt_f32_e32 vcc, s42, v70
	s_nop 1
	v_cndmask_b32_e32 v70, v70, v71, vcc
	v_rsq_f32_e32 v70, v70
	s_nop 0
	v_mul_f32_e32 v71, 0x45800000, v70
	v_cndmask_b32_e32 v70, v70, v71, vcc
	v_pk_mul_f32 v[80:81], v[80:81], v[70:71] op_sel_hi:[1,0]
	s_nop 0
	v_pk_fma_f32 v[80:81], v[76:77], v[80:81], v[78:79]
	s_nop 0
	v_mul_f32_e32 v66, 0xbfb8aa3b, v80
	v_exp_f32_e32 v71, v66
	s_nop 0
	v_pk_mul_f32 v[66:67], v[82:83], v[70:71] op_sel_hi:[1,0]
	s_nop 0
	v_pk_fma_f32 v[66:67], v[68:69], v[66:67], v[72:73]
	s_nop 0
	v_mul_f32_e32 v70, 0xbfb8aa3b, v66
	v_exp_f32_e32 v82, v70
	v_add_f32_e32 v70, 1.0, v71
	v_rcp_f32_e32 v70, v70
	v_add_f32_e32 v71, 1.0, v82
	v_mul_f32_e32 v82, 0xbfb8aa3b, v81
	v_exp_f32_e32 v83, v82
	v_mul_f32_e32 v82, 0xbfb8aa3b, v67
	v_exp_f32_e32 v84, v82
	v_rcp_f32_e32 v82, v71
	v_add_f32_e32 v71, 1.0, v83
	v_rcp_f32_e32 v71, v71
	v_add_f32_e32 v83, 1.0, v84
	v_rcp_f32_e32 v83, v83
	v_pk_mul_f32 v[70:71], v[80:81], v[70:71]
	s_nop 0
	v_and_b32_sdwa v80, v71, v112 dst_sel:DWORD dst_unused:UNUSED_PAD src0_sel:WORD_1 src1_sel:DWORD
	v_pk_mul_f32 v[66:67], v[66:67], v[82:83]
	v_and_b32_sdwa v81, v70, v112 dst_sel:DWORD dst_unused:UNUSED_PAD src0_sel:WORD_1 src1_sel:DWORD
	v_add3_u32 v70, v70, v81, s43
	v_add3_u32 v71, v71, v80, s43
	v_and_b32_sdwa v80, v67, v112 dst_sel:DWORD dst_unused:UNUSED_PAD src0_sel:WORD_1 src1_sel:DWORD
	v_and_b32_sdwa v81, v66, v112 dst_sel:DWORD dst_unused:UNUSED_PAD src0_sel:WORD_1 src1_sel:DWORD
	v_add3_u32 v67, v67, v80, s43
	v_add3_u32 v66, v66, v81, s43
	v_and_b32_e32 v67, 0xffff0000, v67
	v_and_b32_e32 v66, 0xffff0000, v66
	v_or_b32_sdwa v67, v67, v71 dst_sel:DWORD dst_unused:UNUSED_PAD src0_sel:DWORD src1_sel:WORD_1
	v_or_b32_sdwa v66, v66, v70 dst_sel:DWORD dst_unused:UNUSED_PAD src0_sel:DWORD src1_sel:WORD_1
	v_mad_u64_u32 v[70:71], s[4:5], v87, s45, v[74:75]
	ds_write_b64 v70, v[66:67]
	ds_read_b128 v[80:83], v88 offset:2048
	s_waitcnt lgkmcnt(0)
	v_mov_b32_e32 v66, v81
	v_mov_b32_e32 v67, v82
	v_mov_b32_e32 v84, v80
	v_mov_b32_e32 v85, v83
	v_pk_add_f32 v[66:67], v[66:67], v[84:85]
	s_nop 0
	v_add_f32_e32 v66, v66, v67
	s_waitcnt lgkmcnt(0)
	s_nop 1
	v_add_f32_dpp v66, v66, v66 quad_perm:[1,0,3,2] row_mask:0xf bank_mask:0xf
	s_waitcnt lgkmcnt(0)
	s_nop 1
	v_add_f32_dpp v66, v66, v66 quad_perm:[2,3,0,1] row_mask:0xf bank_mask:0xf
	s_waitcnt lgkmcnt(0)
	s_nop 1
	v_add_f32_dpp v66, v66, v66 row_half_mirror row_mask:0xf bank_mask:0xf
	s_waitcnt lgkmcnt(0)
	s_nop 1
	v_add_f32_dpp v66, v66, v66 row_mirror row_mask:0xf bank_mask:0xf
	s_waitcnt lgkmcnt(0)
	v_mov_b32_e32 v67, v66
	v_mov_b32_e32 v254, v66
	s_nop 1
	v_permlane16_swap_b32 v67, v254
	v_add_f32_e32 v66, v67, v254
	s_waitcnt lgkmcnt(0)
	v_mov_b32_e32 v67, v66
	v_mov_b32_e32 v254, v66
	s_nop 1
	v_permlane32_swap_b32 v67, v254
	v_add_f32_e32 v71, v67, v254
	v_fmamk_f32 v67, v71, 0xbb800000, v81
	v_fmamk_f32 v66, v71, 0xbb800000, v80
	v_fmamk_f32 v83, v71, 0xbb800000, v83
	v_fmac_f32_e32 v82, 0xbb800000, v71
	v_pk_mul_f32 v[80:81], v[82:83], v[82:83]
	v_pk_mul_f32 v[84:85], v[66:67], v[66:67]
	s_nop 0
	v_pk_mov_b32 v[86:87], v[84:85], v[80:81] op_sel:[1,0]
	v_mov_b32_e32 v85, v81
	v_pk_add_f32 v[80:81], v[86:87], v[84:85]
	s_nop 0
	v_add_f32_e32 v71, v80, v81
	v_mov_b32_e32 v80, v66
	v_mov_b32_e32 v81, v82
	v_mov_b32_e32 v82, v67
	s_waitcnt lgkmcnt(0)
	s_nop 1
	v_add_f32_dpp v71, v71, v71 quad_perm:[1,0,3,2] row_mask:0xf bank_mask:0xf
	s_waitcnt lgkmcnt(0)
	s_nop 1
	v_add_f32_dpp v71, v71, v71 quad_perm:[2,3,0,1] row_mask:0xf bank_mask:0xf
	s_waitcnt lgkmcnt(0)
	s_nop 1
	v_add_f32_dpp v71, v71, v71 row_half_mirror row_mask:0xf bank_mask:0xf
	s_waitcnt lgkmcnt(0)
	s_nop 1
	v_add_f32_dpp v71, v71, v71 row_mirror row_mask:0xf bank_mask:0xf
	s_waitcnt lgkmcnt(0)
	v_mov_b32_e32 v74, v71
	v_mov_b32_e32 v254, v71
	s_nop 1
	v_permlane16_swap_b32 v74, v254
	v_add_f32_e32 v71, v74, v254
	s_waitcnt lgkmcnt(0)
	v_mov_b32_e32 v74, v71
	v_mov_b32_e32 v254, v71
	s_nop 1
	v_permlane32_swap_b32 v74, v254
	v_add_f32_e32 v71, v74, v254
	v_fmamk_f32 v71, v71, 0x3b800000, v111
	v_mul_f32_e32 v74, 0x4b800000, v71
	v_cmp_gt_f32_e32 vcc, s42, v71
	s_nop 1
	v_cndmask_b32_e32 v71, v71, v74, vcc
	v_rsq_f32_e32 v71, v71
	s_nop 0
	v_mul_f32_e32 v74, 0x45800000, v71
	v_cndmask_b32_e32 v74, v71, v74, vcc
	v_pk_mul_f32 v[80:81], v[80:81], v[74:75] op_sel_hi:[1,0]
	s_nop 0
	v_pk_fma_f32 v[80:81], v[76:77], v[80:81], v[78:79]
	s_nop 0
	v_mul_f32_e32 v66, 0xbfb8aa3b, v80
	v_exp_f32_e32 v71, v66
	v_pk_mul_f32 v[66:67], v[82:83], v[74:75] op_sel_hi:[1,0]
	v_add_f32_e32 v71, 1.0, v71
	v_pk_fma_f32 v[66:67], v[68:69], v[66:67], v[72:73]
	v_rcp_f32_e32 v82, v71
	v_mul_f32_e32 v74, 0xbfb8aa3b, v66
	v_exp_f32_e32 v74, v74
	v_mul_f32_e32 v83, 0xbfb8aa3b, v67
	v_exp_f32_e32 v85, v83
	v_add_f32_e32 v71, 1.0, v74
	v_mul_f32_e32 v74, 0xbfb8aa3b, v81
	v_exp_f32_e32 v74, v74
	v_rcp_f32_e32 v84, v71
	v_add_f32_e32 v71, 1.0, v74
	v_rcp_f32_e32 v83, v71
	v_add_f32_e32 v71, 1.0, v85
	v_rcp_f32_e32 v85, v71
	v_pk_mul_f32 v[80:81], v[80:81], v[82:83]
	s_nop 0
	v_and_b32_sdwa v71, v81, v112 dst_sel:DWORD dst_unused:UNUSED_PAD src0_sel:WORD_1 src1_sel:DWORD
	v_pk_mul_f32 v[66:67], v[66:67], v[84:85]
	v_and_b32_sdwa v74, v80, v112 dst_sel:DWORD dst_unused:UNUSED_PAD src0_sel:WORD_1 src1_sel:DWORD
	v_add3_u32 v74, v80, v74, s43
	v_add3_u32 v71, v81, v71, s43
	v_and_b32_sdwa v80, v67, v112 dst_sel:DWORD dst_unused:UNUSED_PAD src0_sel:WORD_1 src1_sel:DWORD
	v_and_b32_sdwa v81, v66, v112 dst_sel:DWORD dst_unused:UNUSED_PAD src0_sel:WORD_1 src1_sel:DWORD
	v_add3_u32 v67, v67, v80, s43
	v_add3_u32 v66, v66, v81, s43
	v_and_b32_e32 v67, 0xffff0000, v67
	v_and_b32_e32 v66, 0xffff0000, v66
	v_or_b32_sdwa v67, v67, v71 dst_sel:DWORD dst_unused:UNUSED_PAD src0_sel:DWORD src1_sel:WORD_1
	v_or_b32_sdwa v66, v66, v74 dst_sel:DWORD dst_unused:UNUSED_PAD src0_sel:DWORD src1_sel:WORD_1
	ds_write_b64 v70, v[66:67] offset:528
	ds_read_b128 v[80:83], v88 offset:3072
	s_waitcnt lgkmcnt(0)
	v_mov_b32_e32 v66, v81
	v_mov_b32_e32 v67, v82
	v_mov_b32_e32 v84, v80
	v_mov_b32_e32 v85, v83
	v_pk_add_f32 v[66:67], v[66:67], v[84:85]
	s_nop 0
	v_add_f32_e32 v66, v66, v67
	s_waitcnt lgkmcnt(0)
	s_nop 1
	v_add_f32_dpp v66, v66, v66 quad_perm:[1,0,3,2] row_mask:0xf bank_mask:0xf
	s_waitcnt lgkmcnt(0)
	s_nop 1
	v_add_f32_dpp v66, v66, v66 quad_perm:[2,3,0,1] row_mask:0xf bank_mask:0xf
	s_waitcnt lgkmcnt(0)
	s_nop 1
	v_add_f32_dpp v66, v66, v66 row_half_mirror row_mask:0xf bank_mask:0xf
	s_waitcnt lgkmcnt(0)
	s_nop 1
	v_add_f32_dpp v66, v66, v66 row_mirror row_mask:0xf bank_mask:0xf
	s_waitcnt lgkmcnt(0)
	v_mov_b32_e32 v67, v66
	v_mov_b32_e32 v254, v66
	s_nop 1
	v_permlane16_swap_b32 v67, v254
	v_add_f32_e32 v66, v67, v254
	s_waitcnt lgkmcnt(0)
	v_mov_b32_e32 v67, v66
	v_mov_b32_e32 v254, v66
	s_nop 1
	v_permlane32_swap_b32 v67, v254
	v_add_f32_e32 v71, v67, v254
	v_fmamk_f32 v67, v71, 0xbb800000, v81
	v_fmamk_f32 v66, v71, 0xbb800000, v80
	v_fmamk_f32 v83, v71, 0xbb800000, v83
	v_fmac_f32_e32 v82, 0xbb800000, v71
	v_pk_mul_f32 v[80:81], v[82:83], v[82:83]
	v_pk_mul_f32 v[84:85], v[66:67], v[66:67]
	s_nop 0
	v_pk_mov_b32 v[86:87], v[84:85], v[80:81] op_sel:[1,0]
	v_mov_b32_e32 v85, v81
	v_pk_add_f32 v[80:81], v[86:87], v[84:85]
	s_nop 0
	v_add_f32_e32 v71, v80, v81
	v_mov_b32_e32 v80, v66
	v_mov_b32_e32 v81, v82
	v_mov_b32_e32 v82, v67
	s_waitcnt lgkmcnt(0)
	s_nop 1
	v_add_f32_dpp v71, v71, v71 quad_perm:[1,0,3,2] row_mask:0xf bank_mask:0xf
	s_waitcnt lgkmcnt(0)
	s_nop 1
	v_add_f32_dpp v71, v71, v71 quad_perm:[2,3,0,1] row_mask:0xf bank_mask:0xf
	s_waitcnt lgkmcnt(0)
	s_nop 1
	v_add_f32_dpp v71, v71, v71 row_half_mirror row_mask:0xf bank_mask:0xf
	s_waitcnt lgkmcnt(0)
	s_nop 1
	v_add_f32_dpp v71, v71, v71 row_mirror row_mask:0xf bank_mask:0xf
	s_waitcnt lgkmcnt(0)
	v_mov_b32_e32 v74, v71
	v_mov_b32_e32 v254, v71
	s_nop 1
	v_permlane16_swap_b32 v74, v254
	v_add_f32_e32 v71, v74, v254
	s_waitcnt lgkmcnt(0)
	v_mov_b32_e32 v74, v71
	v_mov_b32_e32 v254, v71
	s_nop 1
	v_permlane32_swap_b32 v74, v254
	v_add_f32_e32 v71, v74, v254
	v_fmamk_f32 v71, v71, 0x3b800000, v111
	v_mul_f32_e32 v74, 0x4b800000, v71
	v_cmp_gt_f32_e32 vcc, s42, v71
	s_nop 1
	v_cndmask_b32_e32 v71, v71, v74, vcc
	v_rsq_f32_e32 v71, v71
	s_nop 0
	v_mul_f32_e32 v74, 0x45800000, v71
	v_cndmask_b32_e32 v74, v71, v74, vcc
	v_pk_mul_f32 v[80:81], v[80:81], v[74:75] op_sel_hi:[1,0]
	s_nop 0
	v_pk_fma_f32 v[76:77], v[76:77], v[80:81], v[78:79]
	s_nop 0
	v_mul_f32_e32 v66, 0xbfb8aa3b, v76
	v_exp_f32_e32 v71, v66
	v_pk_mul_f32 v[66:67], v[82:83], v[74:75] op_sel_hi:[1,0]
	v_and_b32_e32 v74, 15, v114
	v_pk_fma_f32 v[66:67], v[68:69], v[66:67], v[72:73]
	s_nop 0
	v_mul_f32_e32 v68, 0xbfb8aa3b, v66
	v_exp_f32_e32 v69, v68
	v_add_f32_e32 v68, 1.0, v71
	v_mul_f32_e32 v71, 0xbfb8aa3b, v77
	v_exp_f32_e32 v71, v71
	v_mul_f32_e32 v72, 0xbfb8aa3b, v67
	v_exp_f32_e32 v73, v72
	v_add_f32_e32 v69, 1.0, v69
	v_rcp_f32_e32 v72, v69
	v_add_f32_e32 v69, 1.0, v71
	v_rcp_f32_e32 v68, v68
	v_rcp_f32_e32 v69, v69
	v_add_f32_e32 v71, 1.0, v73
	v_rcp_f32_e32 v73, v71
	v_pk_mul_f32 v[68:69], v[76:77], v[68:69]
	s_nop 0
	v_and_b32_sdwa v71, v69, v112 dst_sel:DWORD dst_unused:UNUSED_PAD src0_sel:WORD_1 src1_sel:DWORD
	v_pk_mul_f32 v[66:67], v[66:67], v[72:73]
	v_and_b32_sdwa v72, v68, v112 dst_sel:DWORD dst_unused:UNUSED_PAD src0_sel:WORD_1 src1_sel:DWORD
	v_add3_u32 v68, v68, v72, s43
	v_add3_u32 v69, v69, v71, s43
	v_and_b32_sdwa v71, v67, v112 dst_sel:DWORD dst_unused:UNUSED_PAD src0_sel:WORD_1 src1_sel:DWORD
	v_and_b32_sdwa v72, v66, v112 dst_sel:DWORD dst_unused:UNUSED_PAD src0_sel:WORD_1 src1_sel:DWORD
	v_add3_u32 v67, v67, v71, s43
	v_add3_u32 v66, v66, v72, s43
	v_and_b32_e32 v67, 0xffff0000, v67
	v_and_b32_e32 v66, 0xffff0000, v66
	v_or_b32_sdwa v67, v67, v69 dst_sel:DWORD dst_unused:UNUSED_PAD src0_sel:DWORD src1_sel:WORD_1
	v_or_b32_sdwa v66, v66, v68 dst_sel:DWORD dst_unused:UNUSED_PAD src0_sel:DWORD src1_sel:WORD_1
	ds_write_b64 v70, v[66:67] offset:1056
	v_and_b32_e32 v66, 48, v114
	v_mul_u32_u24_e32 v67, 0x210, v74
	v_add3_u32 v100, s41, v66, v67
	s_waitcnt lgkmcnt(0)
	s_barrier
	ds_read_b128 v[66:69], v100
	ds_read_b128 v[70:73], v100 offset:64
	ds_read_b128 v[80:83], v100 offset:8448
	ds_read_b128 v[84:87], v100 offset:8512
	s_waitcnt lgkmcnt(3)
	v_mfma_f32_16x16x32_bf16 v[76:79], v[2:5], v[66:69], 0
	s_waitcnt lgkmcnt(1)
	v_mfma_f32_16x16x32_bf16 v[88:91], v[2:5], v[80:83], 0
	v_mfma_f32_16x16x32_bf16 v[66:69], v[34:37], v[66:69], 0
	v_mfma_f32_16x16x32_bf16 v[80:83], v[34:37], v[80:83], 0
	v_mfma_f32_16x16x32_bf16 v[76:79], v[6:9], v[70:73], v[76:79]
	s_waitcnt lgkmcnt(0)
	v_mfma_f32_16x16x32_bf16 v[88:91], v[6:9], v[84:87], v[88:91]
	v_mfma_f32_16x16x32_bf16 v[66:69], v[38:41], v[70:73], v[66:69]
	v_mfma_f32_16x16x32_bf16 v[70:73], v[38:41], v[84:87], v[80:83]
	s_nop 2
	ds_read_b128 v[80:83], v100 offset:128
	ds_read_b128 v[84:87], v100 offset:192
	ds_read_b128 v[92:95], v100 offset:8576
	ds_read_b128 v[96:99], v100 offset:8640
	s_waitcnt lgkmcnt(3)
	v_mfma_f32_16x16x32_bf16 v[76:79], v[10:13], v[80:83], v[76:79]
	s_waitcnt lgkmcnt(1)
	v_mfma_f32_16x16x32_bf16 v[88:91], v[10:13], v[92:95], v[88:91]
	v_mfma_f32_16x16x32_bf16 v[66:69], v[42:45], v[80:83], v[66:69]
	v_mfma_f32_16x16x32_bf16 v[70:73], v[42:45], v[92:95], v[70:73]
	v_mfma_f32_16x16x32_bf16 v[76:79], v[14:17], v[84:87], v[76:79]
	s_waitcnt lgkmcnt(0)
	v_mfma_f32_16x16x32_bf16 v[80:83], v[14:17], v[96:99], v[88:91]
	v_mfma_f32_16x16x32_bf16 v[66:69], v[46:49], v[84:87], v[66:69]
	ds_read_b128 v[84:87], v100 offset:256
	s_nop 0
	ds_read_b128 v[88:91], v100 offset:320
	v_mfma_f32_16x16x32_bf16 v[70:73], v[46:49], v[96:99], v[70:73]
	ds_read_b128 v[92:95], v100 offset:8704
	ds_read_b128 v[96:99], v100 offset:8768
	s_waitcnt lgkmcnt(3)
	v_mfma_f32_16x16x32_bf16 v[76:79], v[18:21], v[84:87], v[76:79]
	v_mfma_f32_16x16x32_bf16 v[66:69], v[50:53], v[84:87], v[66:69]
	s_waitcnt lgkmcnt(1)
	v_mfma_f32_16x16x32_bf16 v[80:83], v[18:21], v[92:95], v[80:83]
	v_mfma_f32_16x16x32_bf16 v[70:73], v[50:53], v[92:95], v[70:73]
	v_mfma_f32_16x16x32_bf16 v[76:79], v[22:25], v[88:91], v[76:79]
	v_mfma_f32_16x16x32_bf16 v[66:69], v[54:57], v[88:91], v[66:69]
	ds_read_b128 v[84:87], v100 offset:384
	ds_read_b128 v[88:91], v100 offset:448
	s_waitcnt lgkmcnt(2)
	v_mfma_f32_16x16x32_bf16 v[80:83], v[22:25], v[96:99], v[80:83]
	v_mfma_f32_16x16x32_bf16 v[70:73], v[54:57], v[96:99], v[70:73]
	ds_read_b128 v[92:95], v100 offset:8832
	ds_read_b128 v[96:99], v100 offset:8896
	s_waitcnt lgkmcnt(3)
	v_mfma_f32_16x16x32_bf16 v[76:79], v[26:29], v[84:87], v[76:79]
	v_mfma_f32_16x16x32_bf16 v[66:69], v[58:61], v[84:87], v[66:69]
	v_lshrrev_b32_e32 v84, 2, v114
	v_and_b32_e32 v84, 12, v84
	s_waitcnt lgkmcnt(1)
	v_mfma_f32_16x16x32_bf16 v[80:83], v[26:29], v[92:95], v[80:83]
	v_mfma_f32_16x16x32_bf16 v[70:73], v[58:61], v[92:95], v[70:73]
	v_lshl_or_b32 v92, v113, 5, v84
	v_ashrrev_i32_e32 v93, 31, v92
	v_lshl_add_u64 v[94:95], v[92:93], 2, s[10:11]
	v_mfma_f32_16x16x32_bf16 v[76:79], v[30:33], v[88:91], v[76:79]
	v_mfma_f32_16x16x32_bf16 v[66:69], v[62:65], v[88:91], v[66:69]
	v_add_u32_e32 v88, s3, v74
	s_add_i32 s3, s3, s28
	s_cmpk_lt_i32 s46, 0x400
	s_waitcnt lgkmcnt(0)
	v_mfma_f32_16x16x32_bf16 v[80:83], v[30:33], v[96:99], v[80:83]
	s_nop 0
	v_pk_add_f32 v[78:79], v[78:79], v[184:185]
	v_pk_add_f32 v[76:77], v[76:77], v[182:183]
	v_and_b32_sdwa v74, v78, v112 dst_sel:DWORD dst_unused:UNUSED_PAD src0_sel:WORD_1 src1_sel:DWORD
	v_and_b32_sdwa v89, v76, v112 dst_sel:DWORD dst_unused:UNUSED_PAD src0_sel:WORD_1 src1_sel:DWORD
	v_add3_u32 v76, v76, v89, s43
	v_add3_u32 v74, v78, v74, s43
	v_and_b32_sdwa v78, v79, v112 dst_sel:DWORD dst_unused:UNUSED_PAD src0_sel:WORD_1 src1_sel:DWORD
	v_and_b32_sdwa v89, v77, v112 dst_sel:DWORD dst_unused:UNUSED_PAD src0_sel:WORD_1 src1_sel:DWORD
	v_add3_u32 v78, v79, v78, s43
	v_add3_u32 v77, v77, v89, s43
	v_and_b32_e32 v78, 0xffff0000, v78
	v_and_b32_e32 v79, 0xffff0000, v77
	v_ashrrev_i32_e32 v89, 31, v88
	v_or_b32_sdwa v77, v78, v74 dst_sel:DWORD dst_unused:UNUSED_PAD src0_sel:DWORD src1_sel:WORD_1
	v_or_b32_sdwa v76, v79, v76 dst_sel:DWORD dst_unused:UNUSED_PAD src0_sel:DWORD src1_sel:WORD_1
	v_lshlrev_b64 v[78:79], 11, v[88:89]
	v_lshl_add_u64 v[78:79], s[88:89], 0, v[78:79]
	v_lshl_add_u64 v[90:91], v[78:79], 0, s[24:25]
	v_lshlrev_b64 v[78:79], 1, v[92:93]
	v_lshl_add_u64 v[100:101], v[90:91], 0, v[78:79]
	v_pk_add_f32 v[82:83], v[82:83], v[184:185]
	v_pk_add_f32 v[80:81], v[80:81], v[182:183]
	global_store_dwordx2 v[100:101], v[76:77], off
	v_and_b32_sdwa v74, v82, v112 dst_sel:DWORD dst_unused:UNUSED_PAD src0_sel:WORD_1 src1_sel:DWORD
	v_and_b32_sdwa v77, v80, v112 dst_sel:DWORD dst_unused:UNUSED_PAD src0_sel:WORD_1 src1_sel:DWORD
	v_add3_u32 v77, v80, v77, s43
	v_add3_u32 v74, v82, v74, s43
	v_and_b32_sdwa v80, v83, v112 dst_sel:DWORD dst_unused:UNUSED_PAD src0_sel:WORD_1 src1_sel:DWORD
	v_and_b32_sdwa v82, v81, v112 dst_sel:DWORD dst_unused:UNUSED_PAD src0_sel:WORD_1 src1_sel:DWORD
	v_add3_u32 v80, v83, v80, s43
	v_add3_u32 v81, v81, v82, s43
	v_add_u32_e32 v76, 16, v88
	v_and_b32_e32 v80, 0xffff0000, v80
	v_and_b32_e32 v82, 0xffff0000, v81
	v_or_b32_sdwa v81, v80, v74 dst_sel:DWORD dst_unused:UNUSED_PAD src0_sel:DWORD src1_sel:WORD_1
	v_or_b32_sdwa v80, v82, v77 dst_sel:DWORD dst_unused:UNUSED_PAD src0_sel:DWORD src1_sel:WORD_1
	v_ashrrev_i32_e32 v77, 31, v76
	v_lshlrev_b64 v[76:77], 11, v[76:77]
	v_lshl_add_u64 v[76:77], s[88:89], 0, v[76:77]
	v_lshl_add_u64 v[82:83], v[76:77], 0, s[24:25]
	v_lshl_add_u64 v[76:77], v[82:83], 0, v[78:79]
	global_store_dwordx2 v[76:77], v[80:81], off
	v_mfma_f32_16x16x32_bf16 v[70:73], v[62:65], v[96:99], v[70:73]
	v_or_b32_e32 v80, 16, v92
	v_ashrrev_i32_e32 v81, 31, v80
	v_pk_add_f32 v[68:69], v[68:69], v[188:189]
	v_pk_add_f32 v[66:67], v[66:67], v[186:187]
	v_and_b32_sdwa v74, v68, v112 dst_sel:DWORD dst_unused:UNUSED_PAD src0_sel:WORD_1 src1_sel:DWORD
	v_and_b32_sdwa v84, v66, v112 dst_sel:DWORD dst_unused:UNUSED_PAD src0_sel:WORD_1 src1_sel:DWORD
	v_add3_u32 v68, v68, v74, s43
	v_and_b32_sdwa v74, v69, v112 dst_sel:DWORD dst_unused:UNUSED_PAD src0_sel:WORD_1 src1_sel:DWORD
	v_add3_u32 v66, v66, v84, s43
	v_and_b32_sdwa v84, v67, v112 dst_sel:DWORD dst_unused:UNUSED_PAD src0_sel:WORD_1 src1_sel:DWORD
	v_add3_u32 v69, v69, v74, s43
	v_add3_u32 v67, v67, v84, s43
	v_and_b32_e32 v69, 0xffff0000, v69
	v_and_b32_e32 v74, 0xffff0000, v67
	v_or_b32_sdwa v67, v69, v68 dst_sel:DWORD dst_unused:UNUSED_PAD src0_sel:DWORD src1_sel:WORD_1
	v_lshlrev_b64 v[68:69], 1, v[80:81]
	v_or_b32_sdwa v66, v74, v66 dst_sel:DWORD dst_unused:UNUSED_PAD src0_sel:DWORD src1_sel:WORD_1
	v_lshl_add_u64 v[80:81], v[90:91], 0, v[68:69]
	global_store_dwordx2 v[80:81], v[66:67], off
	v_pk_add_f32 v[66:67], v[72:73], v[188:189]
	v_pk_add_f32 v[70:71], v[70:71], v[186:187]
	v_and_b32_sdwa v72, v66, v112 dst_sel:DWORD dst_unused:UNUSED_PAD src0_sel:WORD_1 src1_sel:DWORD
	v_and_b32_sdwa v73, v70, v112 dst_sel:DWORD dst_unused:UNUSED_PAD src0_sel:WORD_1 src1_sel:DWORD
	v_add3_u32 v70, v70, v73, s43
	v_add3_u32 v66, v66, v72, s43
	v_and_b32_sdwa v72, v67, v112 dst_sel:DWORD dst_unused:UNUSED_PAD src0_sel:WORD_1 src1_sel:DWORD
	v_and_b32_sdwa v73, v71, v112 dst_sel:DWORD dst_unused:UNUSED_PAD src0_sel:WORD_1 src1_sel:DWORD
	v_add3_u32 v67, v67, v72, s43
	v_add3_u32 v71, v71, v73, s43
	v_and_b32_e32 v67, 0xffff0000, v67
	v_and_b32_e32 v71, 0xffff0000, v71
	v_or_b32_sdwa v67, v67, v66 dst_sel:DWORD dst_unused:UNUSED_PAD src0_sel:DWORD src1_sel:WORD_1
	v_or_b32_sdwa v66, v71, v70 dst_sel:DWORD dst_unused:UNUSED_PAD src0_sel:DWORD src1_sel:WORD_1
	v_lshl_add_u64 v[68:69], v[82:83], 0, v[68:69]
	global_store_dwordx2 v[68:69], v[66:67], off
	s_barrier
	s_cbranch_scc0 .LBB0_1997
